# stack14: stack12 + K-loop LDS-DMA loads in saddr form (scalar base + fixed lane offsets, no per-step VALU address updates)
# speedup vs baseline: 1.0113x; 1.0113x over previous
; #define G_LANE_SETUP() \
;     int tid_ = threadIdx.x; \
;     asm volatile("" : "+v"(tid_));    \
;     const int wid = tid_ >> 6, lane = tid_ & 63, wr = wid >> 2, wc = wid & 3, fr = lane & 15, fq = lane >> 4; \
;     unsigned soff[4];        \
;     _Pragma("unroll") for (int i = 0; i < 4; ++i) { int sR, sC; stage_rc2(wid * 1024 + i * 8192 + lane * 16, sR, sC); soff[i] = (unsigned)(sR * K + sC) * 2u; }
; #define G_STAGE_A(Ap, buf, kt) do { const char* ab_ = (const char*)(Ap) + (size_t)(kt) * 128; \
;       _Pragma("unroll") for (int i = 0; i < 4; ++i) \
;         __builtin_amdgcn_global_load_lds((const unsigned*)(ab_ + soff[i]), (LDSP unsigned*)(G_SA(buf) + wid * 1024 + i * 8192), 16, 0, 0); } while (0)
; #define G_SB0() __builtin_amdgcn_sched_barrier(0)
; template <int EK>
; DI void gemm_stream(const Params& p, int l, const bf16_t* __restrict__ A, const bf16_t* __restrict__ Bt, int M, int N, int K, ldsp_t shm) {
;     ...
;         G_LANE_SETUP();
;         const int aoff = lds_byte2(wr * 128 + fr, fq * 8), boff = lds_byte2(wc * 64 + fr, fq * 8);
;         f32x4 acc[8][4];
; #pragma unroll
;         for (int m = 0; m < 8; ++m)
; #pragma unroll
;             for (int n = 0; n < 4; ++n) acc[m][n] = (f32x4){0.f, 0.f, 0.f, 0.f};
;         const int Ln = L + gridDim.x;
;         const bool has_next = Ln < nwg;
;         int pm2 = pm, pn2 = pn;
;         if (has_next) tile_coords(Ln, nM, nN, pm2, pn2);
;         const bf16_t* Ab2 = A + (size_t)pm2 * 256 * K;
;         const bf16_t* Bb2 = Bt + (size_t)pn2 * 256 * K;
;         bf16x8 Aa[4], Ab_[4], Bk0[4], Bk1[4];
;     ...
;         for (int t = 0; t < nt; ++t) {
;             const int cur = t & 1;
;             G_RDA(Aa, cur, 0, 0); G_RDB(Bk0, cur, 0);
;             if (t + 1 < nt) G_STAGE_B(Bb, cur ^ 1, t + 1);
;             else if (has_next) G_STAGE_B(Bb2, cur ^ 1, 0);
;             G_SB0();
;             if (t > 0) G_MMA(Ab_, Bk1, 1);
;             G_SB0();
;             if (t + 1 < nt) G_STAGE_A(Ab, cur ^ 1, t + 1);
;             else if (has_next) G_STAGE_A(Ab2, cur ^ 1, 0);
;             G_RDA(Ab_, cur, 0, 1);
;             G_MMA(Aa, Bk0, 0); G_SB0();
;             G_RDA(Aa, cur, 1, 0); G_RDB(Bk1, cur, 1);
;             G_MMA(Ab_, Bk0, 1); G_SB0();
;             G_RDA(Ab_, cur, 1, 1);
;             G_MMA(Aa, Bk1, 0); G_SB0();
.LBB0_110:
	v_lshlrev_b32_e32 v0, 4, v160
	v_and_b32_e32 v1, 32, v160
	v_bfe_u32 v161, v160, 2, 4
	v_and_b32_e32 v190, 64, v160
	v_bitop3_b32 v191, v0, v1, 48 bitop3:0x6c
	v_lshrrev_b32_e32 v2, 3, v160
	v_or_b32_e32 v1, v191, v190
	v_and_or_b32 v2, v2, s86, v161
	v_add_u32_e32 v200, 0x2000, v0
	v_lshl_or_b32 v192, v2, 11, v1
	v_lshrrev_b32_e32 v2, 7, v200
	v_and_or_b32 v2, v2, s86, v161
	v_add_u32_e32 v201, 0x4000, v0
	v_add_u32_e32 v221, 0x6000, v0
	v_and_b32_e32 v220, 0xfffffc00, v0
	v_lshl_or_b32 v194, v2, 11, v1
	v_lshrrev_b32_e32 v2, 7, v201
	v_lshrrev_b32_e32 v0, 7, v221
	v_and_or_b32 v2, v2, s86, v161
	v_and_or_b32 v0, v0, s86, v161
	v_lshl_or_b32 v196, v2, 11, v1
	v_lshl_or_b32 v198, v0, 11, v1
	v_lshlrev_b32_e32 v1, 6, v160
	v_lshlrev_b32_e32 v4, 2, v160
	v_and_b32_e32 v0, 48, v160
	v_and_b32_e32 v2, 0x3c0, v1
	v_and_b32_e32 v4, 32, v4
	v_bitop3_b32 v0, v2, v4, v0 bitop3:0x36
	s_movk_i32 s4, 0xc000
	v_and_or_b32 v218, v1, s4, v0
	s_add_u32 s4, s9, s38
	s_addc_u32 s5, s45, s39
	v_add_u32_e32 v34, 0x18000, v220
	v_lshl_add_u64 v[32:33], s[4:5], 0, v[192:193]
	v_readfirstlane_b32 s35, v34
	v_lshlrev_b32_e32 v3, 7, v160
	v_lshl_add_u64 v[32:33], v[32:33], 0, s[0:1]
	s_mov_b32 m0, s35
	v_mov_b32_e32 v195, v193
	v_add_u32_e32 v34, 0x1a000, v220
	v_and_or_b32 v219, v3, s28, v0
	ds_read_b128 v[0:3], v218
	ds_read_b128 v[4:7], v218 offset:2048
	ds_read_b128 v[8:11], v218 offset:4096
	ds_read_b128 v[12:15], v218 offset:6144
	ds_read_b128 v[16:19], v219 offset:32768
	ds_read_b128 v[20:23], v219 offset:34816
	ds_read_b128 v[24:27], v219 offset:36864
	ds_read_b128 v[28:31], v219 offset:38912
	global_load_lds_dwordx4 v[32:33], off
	v_lshl_add_u64 v[32:33], s[4:5], 0, v[194:195]
	v_readfirstlane_b32 s35, v34
	v_lshl_add_u64 v[32:33], v[32:33], 0, s[0:1]
	s_mov_b32 m0, s35
	v_mov_b32_e32 v197, v193
	v_add_u32_e32 v34, 0x1c000, v220
	global_load_lds_dwordx4 v[32:33], off
	v_lshl_add_u64 v[32:33], s[4:5], 0, v[196:197]
	v_readfirstlane_b32 s35, v34
	v_lshl_add_u64 v[32:33], v[32:33], 0, s[0:1]
	s_mov_b32 m0, s35
	v_mov_b32_e32 v199, v193
	v_add_u32_e32 v34, 0x1e000, v220
	global_load_lds_dwordx4 v[32:33], off
	v_lshl_add_u64 v[32:33], s[4:5], 0, v[198:199]
	v_readfirstlane_b32 s4, v34
	v_lshl_add_u64 v[32:33], v[32:33], 0, s[0:1]
	s_mov_b32 m0, s4
	s_nop 0
	global_load_lds_dwordx4 v[32:33], off
	s_add_u32 s4, s82, s40
	s_addc_u32 s5, s83, s41
	v_add_u32_e32 v34, 0x10000, v220
	v_lshl_add_u64 v[32:33], s[4:5], 0, v[192:193]
	v_readfirstlane_b32 s35, v34
	v_lshl_add_u64 v[32:33], v[32:33], 0, s[0:1]
	s_mov_b32 m0, s35
	v_add_u32_e32 v34, 0x12000, v220
	global_load_lds_dwordx4 v[32:33], off
	v_lshl_add_u64 v[32:33], s[4:5], 0, v[194:195]
	v_readfirstlane_b32 s35, v34
	v_lshl_add_u64 v[32:33], v[32:33], 0, s[0:1]
	s_mov_b32 m0, s35
	v_add_u32_e32 v34, 0x14000, v220
	global_load_lds_dwordx4 v[32:33], off
	v_lshl_add_u64 v[32:33], s[4:5], 0, v[196:197]
	v_readfirstlane_b32 s35, v34
	v_lshl_add_u64 v[32:33], v[32:33], 0, s[0:1]
	s_mov_b32 m0, s35
	v_add_u32_e32 v34, 0x16000, v220
	global_load_lds_dwordx4 v[32:33], off
	v_lshl_add_u64 v[32:33], s[4:5], 0, v[198:199]
	v_readfirstlane_b32 s4, v34
	v_lshl_add_u64 v[32:33], v[32:33], 0, s[0:1]
	s_mov_b32 m0, s4
	s_mov_b32 s35, 0x10000
	global_load_lds_dwordx4 v[32:33], off
	ds_read_b128 v[32:35], v218 offset:8192
	ds_read_b128 v[36:39], v218 offset:10240
	ds_read_b128 v[40:43], v218 offset:12288
	ds_read_b128 v[44:47], v218 offset:14336
	s_setprio 1
	s_waitcnt lgkmcnt(0)
	v_mfma_f32_16x16x32_bf16 v[48:51], v[16:19], v[0:3], 0
	v_mfma_f32_16x16x32_bf16 v[52:55], v[20:23], v[0:3], 0
	v_mfma_f32_16x16x32_bf16 v[162:165], v[24:27], v[0:3], 0
	v_mfma_f32_16x16x32_bf16 v[0:3], v[28:31], v[0:3], 0
	v_mfma_f32_16x16x32_bf16 v[166:169], v[16:19], v[4:7], 0
	v_mfma_f32_16x16x32_bf16 v[170:173], v[20:23], v[4:7], 0
	v_mfma_f32_16x16x32_bf16 v[174:177], v[24:27], v[4:7], 0
	v_mfma_f32_16x16x32_bf16 v[4:7], v[28:31], v[4:7], 0
	v_mfma_f32_16x16x32_bf16 v[178:181], v[16:19], v[8:11], 0
	v_mfma_f32_16x16x32_bf16 v[182:185], v[20:23], v[8:11], 0
	v_mfma_f32_16x16x32_bf16 v[186:189], v[24:27], v[8:11], 0
	v_mfma_f32_16x16x32_bf16 v[8:11], v[28:31], v[8:11], 0
	v_mfma_f32_16x16x32_bf16 v[204:207], v[16:19], v[12:15], 0
	v_mfma_f32_16x16x32_bf16 v[210:213], v[20:23], v[12:15], 0
	v_mfma_f32_16x16x32_bf16 v[214:217], v[24:27], v[12:15], 0
	v_mfma_f32_16x16x32_bf16 v[222:225], v[28:31], v[12:15], 0
	s_setprio 0
	ds_read_b128 v[12:15], v218 offset:1024
	ds_read_b128 v[226:229], v218 offset:3072
	ds_read_b128 v[230:233], v218 offset:5120
	ds_read_b128 v[234:237], v218 offset:7168
	ds_read_b128 v[64:67], v219 offset:33792
	ds_read_b128 v[68:71], v219 offset:35840
	ds_read_b128 v[76:79], v219 offset:37888
	ds_read_b128 v[72:75], v219 offset:39936
	s_setprio 1
	v_mfma_f32_16x16x32_bf16 v[128:131], v[16:19], v[32:35], 0
	v_mfma_f32_16x16x32_bf16 v[124:127], v[20:23], v[32:35], 0
	v_mfma_f32_16x16x32_bf16 v[120:123], v[24:27], v[32:35], 0
	v_mfma_f32_16x16x32_bf16 v[116:119], v[28:31], v[32:35], 0
	v_mfma_f32_16x16x32_bf16 v[112:115], v[16:19], v[36:39], 0
	v_mfma_f32_16x16x32_bf16 v[108:111], v[20:23], v[36:39], 0
	v_mfma_f32_16x16x32_bf16 v[104:107], v[24:27], v[36:39], 0
	v_mfma_f32_16x16x32_bf16 v[100:103], v[28:31], v[36:39], 0
	v_mfma_f32_16x16x32_bf16 v[96:99], v[16:19], v[40:43], 0
	v_mfma_f32_16x16x32_bf16 v[92:95], v[20:23], v[40:43], 0
	v_mfma_f32_16x16x32_bf16 v[88:91], v[24:27], v[40:43], 0
	v_mfma_f32_16x16x32_bf16 v[84:87], v[28:31], v[40:43], 0
	v_mfma_f32_16x16x32_bf16 v[132:135], v[16:19], v[44:47], 0
	v_mfma_f32_16x16x32_bf16 v[136:139], v[20:23], v[44:47], 0
	v_mfma_f32_16x16x32_bf16 v[140:143], v[24:27], v[44:47], 0
	v_mfma_f32_16x16x32_bf16 v[80:83], v[28:31], v[44:47], 0
	s_setprio 0
	ds_read_b128 v[156:159], v218 offset:9216
	ds_read_b128 v[152:155], v218 offset:11264
	ds_read_b128 v[148:151], v218 offset:13312
	ds_read_b128 v[144:147], v218 offset:15360
	s_setprio 1
	s_waitcnt lgkmcnt(0)
; #define WAIT_V0() asm volatile("s_waitcnt vmcnt(0)" ::: "memory")
; #define G_STAGE_A(Ap, buf, kt) do { const char* ab_ = (const char*)(Ap) + (size_t)(kt) * 128; \
;       _Pragma("unroll") for (int i = 0; i < 4; ++i) \
;         __builtin_amdgcn_global_load_lds((const unsigned*)(ab_ + soff[i]), (LDSP unsigned*)(G_SA(buf) + wid * 1024 + i * 8192), 16, 0, 0); } while (0)
; #define G_STAGE_B(Bp, buf, kt) do { const char* bb_ = (const char*)(Bp) + (size_t)(kt) * 128; \
;       _Pragma("unroll") for (int i = 0; i < 4; ++i) \
;         __builtin_amdgcn_global_load_lds((const unsigned*)(bb_ + soff[i]), (LDSP unsigned*)(G_SB(buf) + wid * 1024 + i * 8192), 16, 0, 0); } while (0)
; #define G_RDA(AF, buf, ks, mh) do { _Pragma("unroll") for (int m = 0; m < 4; ++m) AF[m] = *(const LDSP bf16x8*)(G_SA(buf) + aoff + ((mh) * 4 + m) * 2048 + (ks) * 1024); } while (0)
; #define G_RDB(BF, buf, ks) do { _Pragma("unroll") for (int n = 0; n < 4; ++n) BF[n] = *(const LDSP bf16x8*)(G_SB(buf) + boff + n * 2048 + (ks) * 1024); } while (0)
; #define G_MMA(AF, BF, mh) do { __builtin_amdgcn_s_setprio(1); \
;             _Pragma("unroll") for (int m = 0; m < 4; ++m) _Pragma("unroll") for (int n = 0; n < 4; ++n) \
;                 acc[(mh) * 4 + m][n] = __builtin_amdgcn_mfma_f32_16x16x32_bf16(BF[n], AF[m], acc[(mh) * 4 + m][n], 0, 0, 0); \
;             __builtin_amdgcn_s_setprio(0); } while (0)
; template <int EK>
; DI void gemm_stream(const Params& p, int l, const bf16_t* __restrict__ A, const bf16_t* __restrict__ Bt, int M, int N, int K, ldsp_t shm) {
;     ...
;         for (int t = 0; t < nt; ++t) {
;             const int cur = t & 1;
;             G_RDA(Aa, cur, 0, 0); G_RDB(Bk0, cur, 0);
;             if (t + 1 < nt) G_STAGE_B(Bb, cur ^ 1, t + 1);
;             else if (has_next) G_STAGE_B(Bb2, cur ^ 1, 0);
;             G_SB0();
;             if (t > 0) G_MMA(Ab_, Bk1, 1);
;             G_SB0();
;             if (t + 1 < nt) G_STAGE_A(Ab, cur ^ 1, t + 1);
;             else if (has_next) G_STAGE_A(Ab2, cur ^ 1, 0);
;             G_RDA(Ab_, cur, 0, 1);
;             G_MMA(Aa, Bk0, 0); G_SB0();
;             G_RDA(Aa, cur, 1, 0); G_RDB(Bk1, cur, 1);
;             G_MMA(Ab_, Bk0, 1); G_SB0();
;             G_RDA(Ab_, cur, 1, 1);
;             G_MMA(Aa, Bk1, 0); G_SB0();
;             asm volatile("s_waitcnt lgkmcnt(0)" ::: "memory");
;             WAIT_V0(); __syncthreads();
	v_mfma_f32_16x16x32_bf16 v[60:63], v[64:67], v[12:15], v[48:51]
	v_mfma_f32_16x16x32_bf16 v[56:59], v[68:71], v[12:15], v[52:55]
	v_mfma_f32_16x16x32_bf16 v[52:55], v[76:79], v[12:15], v[162:165]
	v_mfma_f32_16x16x32_bf16 v[48:51], v[72:75], v[12:15], v[0:3]
	v_mfma_f32_16x16x32_bf16 v[44:47], v[64:67], v[226:229], v[166:169]
	v_mfma_f32_16x16x32_bf16 v[40:43], v[68:71], v[226:229], v[170:173]
	v_mfma_f32_16x16x32_bf16 v[36:39], v[76:79], v[226:229], v[174:177]
	v_mfma_f32_16x16x32_bf16 v[32:35], v[72:75], v[226:229], v[4:7]
	v_mfma_f32_16x16x32_bf16 v[28:31], v[64:67], v[230:233], v[178:181]
	v_mfma_f32_16x16x32_bf16 v[24:27], v[68:71], v[230:233], v[182:185]
	v_mfma_f32_16x16x32_bf16 v[20:23], v[76:79], v[230:233], v[186:189]
	v_mfma_f32_16x16x32_bf16 v[16:19], v[72:75], v[230:233], v[8:11]
	v_mfma_f32_16x16x32_bf16 v[12:15], v[64:67], v[234:237], v[204:207]
	v_mfma_f32_16x16x32_bf16 v[8:11], v[68:71], v[234:237], v[210:213]
	v_mfma_f32_16x16x32_bf16 v[4:7], v[76:79], v[234:237], v[214:217]
	v_mfma_f32_16x16x32_bf16 v[0:3], v[72:75], v[234:237], v[222:225]
	s_setprio 0
	v_lshlrev_b32_e32 v160, 8, v160
	v_lshlrev_b32_e32 v162, 4, v200
	v_lshlrev_b32_e32 v164, 4, v201
	v_lshlrev_b32_e32 v167, 4, v221
	v_and_or_b32 v160, v160, s90, v191
	v_lshlrev_b32_e32 v166, 11, v161
	s_add_u32 s4, s31, s38
	v_and_or_b32 v162, v162, s90, v191
	v_and_or_b32 v164, v164, s90, v191
	v_and_or_b32 v167, v167, s90, v191
	v_or3_b32 v168, v160, v166, v190
	v_mov_b32_e32 v169, v193
	s_addc_u32 s5, s46, s39
	v_or3_b32 v170, v162, v166, v190
	v_mov_b32_e32 v171, v193
	v_or3_b32 v172, v164, v166, v190
	v_mov_b32_e32 v173, v193
	v_or3_b32 v174, v167, v166, v190
	v_mov_b32_e32 v175, v193
	s_waitcnt lgkmcnt(0)
	v_writelane_b32 v255, s52, 12
	v_writelane_b32 v255, s53, 13
	v_writelane_b32 v255, s64, 14
	v_writelane_b32 v255, s65, 15
	v_writelane_b32 v255, s30, 16
	s_mov_b64 s[64:65], s[4:5]
	v_readlane_b32 s4, v254, 18
	s_waitcnt vmcnt(0)
	s_add_u32 s4, s4, s40
	v_readlane_b32 s5, v254, 19
	s_addc_u32 s5, s5, s41
	s_waitcnt vmcnt(0)
	s_mov_b64 s[52:53], s[4:5]
	s_mov_b64 s[4:5], 0
	v_lshrrev_b32_e32 v164, 6, v252
	v_lshlrev_b32_e32 v164, 10, v164
	s_nop 0
	v_readfirstlane_b32 s30, v164
	v_and_b32_e32 v165, 63, v252
	v_lshlrev_b32_e32 v165, 4, v165
	s_barrier
.LBB0_111:
	s_and_b32 s37, s35, 0x10000
	v_add_u32_e32 v221, s37, v218
	v_or_b32_e32 v226, s37, v219
	s_xor_b32 s37, s37, 0x10000
	s_add_u32 s37, s37, s30
	ds_read_b128 v[176:179], v221
	ds_read_b128 v[180:183], v221 offset:2048
	ds_read_b128 v[184:187], v221 offset:4096
	ds_read_b128 v[188:191], v221 offset:6144
	s_add_u32 m0, s37, 0x8000
	ds_read_b128 v[204:207], v226 offset:32768
	global_load_lds_dwordx4 v168, s[64:65]
	s_add_u32 m0, s37, 0xa000
	ds_read_b128 v[210:213], v226 offset:34816
	global_load_lds_dwordx4 v170, s[64:65]
	s_add_u32 m0, s37, 0xc000
	ds_read_b128 v[214:217], v226 offset:36864
	global_load_lds_dwordx4 v172, s[64:65]
	s_add_u32 m0, s37, 0xe000
	ds_read_b128 v[222:225], v226 offset:38912
	global_load_lds_dwordx4 v174, s[64:65]
	s_setprio 1
	v_mfma_f32_16x16x32_bf16 v[128:131], v[64:67], v[156:159], v[128:131]
	v_mfma_f32_16x16x32_bf16 v[124:127], v[68:71], v[156:159], v[124:127]
	v_mfma_f32_16x16x32_bf16 v[120:123], v[76:79], v[156:159], v[120:123]
	v_mfma_f32_16x16x32_bf16 v[116:119], v[72:75], v[156:159], v[116:119]
	v_mfma_f32_16x16x32_bf16 v[112:115], v[64:67], v[152:155], v[112:115]
	v_mfma_f32_16x16x32_bf16 v[108:111], v[68:71], v[152:155], v[108:111]
	v_mfma_f32_16x16x32_bf16 v[104:107], v[76:79], v[152:155], v[104:107]
	v_mfma_f32_16x16x32_bf16 v[100:103], v[72:75], v[152:155], v[100:103]
	v_mfma_f32_16x16x32_bf16 v[96:99], v[64:67], v[148:151], v[96:99]
	v_mfma_f32_16x16x32_bf16 v[92:95], v[68:71], v[148:151], v[92:95]
	v_mfma_f32_16x16x32_bf16 v[88:91], v[76:79], v[148:151], v[88:91]
	v_mfma_f32_16x16x32_bf16 v[84:87], v[72:75], v[148:151], v[84:87]
	v_mfma_f32_16x16x32_bf16 v[132:135], v[64:67], v[144:147], v[132:135]
	v_mfma_f32_16x16x32_bf16 v[136:139], v[68:71], v[144:147], v[136:139]
	v_mfma_f32_16x16x32_bf16 v[140:143], v[76:79], v[144:147], v[140:143]
	v_mfma_f32_16x16x32_bf16 v[80:83], v[72:75], v[144:147], v[80:83]
	s_setprio 0
	s_add_u32 m0, s37, 0x0
	s_nop 0
	global_load_lds_dwordx4 v168, s[52:53]
	s_add_u32 m0, s37, 0x2000
	s_nop 0
	global_load_lds_dwordx4 v170, s[52:53]
	s_add_u32 m0, s37, 0x4000
	s_nop 0
	global_load_lds_dwordx4 v172, s[52:53]
	s_add_u32 m0, s37, 0x6000
	s_nop 0
	global_load_lds_dwordx4 v174, s[52:53]
	ds_read_b128 v[144:147], v221 offset:8192
	ds_read_b128 v[148:151], v221 offset:10240
	ds_read_b128 v[152:155], v221 offset:12288
	ds_read_b128 v[156:159], v221 offset:14336
	s_setprio 1
	s_waitcnt lgkmcnt(4)
; #define WAIT_V0() asm volatile("s_waitcnt vmcnt(0)" ::: "memory")
; #define G_STAGE_B(Bp, buf, kt) do { const char* bb_ = (const char*)(Bp) + (size_t)(kt) * 128; \
;       _Pragma("unroll") for (int i = 0; i < 4; ++i) \
;         __builtin_amdgcn_global_load_lds((const unsigned*)(bb_ + soff[i]), (LDSP unsigned*)(G_SB(buf) + wid * 1024 + i * 8192), 16, 0, 0); } while (0)
; #define G_RDA(AF, buf, ks, mh) do { _Pragma("unroll") for (int m = 0; m < 4; ++m) AF[m] = *(const LDSP bf16x8*)(G_SA(buf) + aoff + ((mh) * 4 + m) * 2048 + (ks) * 1024); } while (0)
; #define G_RDB(BF, buf, ks) do { _Pragma("unroll") for (int n = 0; n < 4; ++n) BF[n] = *(const LDSP bf16x8*)(G_SB(buf) + boff + n * 2048 + (ks) * 1024); } while (0)
; #define G_MMA(AF, BF, mh) do { __builtin_amdgcn_s_setprio(1); \
;             _Pragma("unroll") for (int m = 0; m < 4; ++m) _Pragma("unroll") for (int n = 0; n < 4; ++n) \
;                 acc[(mh) * 4 + m][n] = __builtin_amdgcn_mfma_f32_16x16x32_bf16(BF[n], AF[m], acc[(mh) * 4 + m][n], 0, 0, 0); \
;             __builtin_amdgcn_s_setprio(0); } while (0)
; #define G_SB0() __builtin_amdgcn_sched_barrier(0)
; template <int EK>
; DI void gemm_stream(const Params& p, int l, const bf16_t* __restrict__ A, const bf16_t* __restrict__ Bt, int M, int N, int K, ldsp_t shm) {
;     ...
;             G_RDA(Aa, cur, 0, 0); G_RDB(Bk0, cur, 0);
;             if (t + 1 < nt) G_STAGE_B(Bb, cur ^ 1, t + 1);
;             else if (has_next) G_STAGE_B(Bb2, cur ^ 1, 0);
;     ...
;             G_MMA(Aa, Bk0, 0); G_SB0();
;             G_RDA(Aa, cur, 1, 0); G_RDB(Bk1, cur, 1);
;             G_MMA(Ab_, Bk0, 1); G_SB0();
;             G_RDA(Ab_, cur, 1, 1);
;             G_MMA(Aa, Bk1, 0); G_SB0();
;             asm volatile("s_waitcnt lgkmcnt(0)" ::: "memory");
;             WAIT_V0(); __syncthreads();
	v_mfma_f32_16x16x32_bf16 v[60:63], v[204:207], v[176:179], v[60:63]
	v_mfma_f32_16x16x32_bf16 v[56:59], v[210:213], v[176:179], v[56:59]
	v_mfma_f32_16x16x32_bf16 v[52:55], v[214:217], v[176:179], v[52:55]
	v_mfma_f32_16x16x32_bf16 v[48:51], v[222:225], v[176:179], v[48:51]
	v_mfma_f32_16x16x32_bf16 v[44:47], v[204:207], v[180:183], v[44:47]
	v_mfma_f32_16x16x32_bf16 v[40:43], v[210:213], v[180:183], v[40:43]
	v_mfma_f32_16x16x32_bf16 v[36:39], v[214:217], v[180:183], v[36:39]
	v_mfma_f32_16x16x32_bf16 v[32:35], v[222:225], v[180:183], v[32:35]
	v_mfma_f32_16x16x32_bf16 v[28:31], v[204:207], v[184:187], v[28:31]
	v_mfma_f32_16x16x32_bf16 v[24:27], v[210:213], v[184:187], v[24:27]
	v_mfma_f32_16x16x32_bf16 v[20:23], v[214:217], v[184:187], v[20:23]
	v_mfma_f32_16x16x32_bf16 v[16:19], v[222:225], v[184:187], v[16:19]
	v_mfma_f32_16x16x32_bf16 v[12:15], v[204:207], v[188:191], v[12:15]
	v_mfma_f32_16x16x32_bf16 v[8:11], v[210:213], v[188:191], v[8:11]
	v_mfma_f32_16x16x32_bf16 v[4:7], v[214:217], v[188:191], v[4:7]
	v_mfma_f32_16x16x32_bf16 v[0:3], v[222:225], v[188:191], v[0:3]
	s_setprio 0
	ds_read_b128 v[176:179], v221 offset:1024
	ds_read_b128 v[180:183], v221 offset:3072
	ds_read_b128 v[184:187], v221 offset:5120
	ds_read_b128 v[188:191], v221 offset:7168
	ds_read_b128 v[64:67], v226 offset:33792
	ds_read_b128 v[68:71], v226 offset:35840
	ds_read_b128 v[76:79], v226 offset:37888
	ds_read_b128 v[72:75], v226 offset:39936
	s_setprio 1
	s_waitcnt lgkmcnt(8)
	v_mfma_f32_16x16x32_bf16 v[128:131], v[204:207], v[144:147], v[128:131]
	v_mfma_f32_16x16x32_bf16 v[124:127], v[210:213], v[144:147], v[124:127]
	v_mfma_f32_16x16x32_bf16 v[120:123], v[214:217], v[144:147], v[120:123]
	v_mfma_f32_16x16x32_bf16 v[116:119], v[222:225], v[144:147], v[116:119]
	v_mfma_f32_16x16x32_bf16 v[112:115], v[204:207], v[148:151], v[112:115]
	v_mfma_f32_16x16x32_bf16 v[108:111], v[210:213], v[148:151], v[108:111]
	v_mfma_f32_16x16x32_bf16 v[104:107], v[214:217], v[148:151], v[104:107]
	v_mfma_f32_16x16x32_bf16 v[100:103], v[222:225], v[148:151], v[100:103]
	v_mfma_f32_16x16x32_bf16 v[96:99], v[204:207], v[152:155], v[96:99]
	v_mfma_f32_16x16x32_bf16 v[92:95], v[210:213], v[152:155], v[92:95]
	v_mfma_f32_16x16x32_bf16 v[88:91], v[214:217], v[152:155], v[88:91]
	v_mfma_f32_16x16x32_bf16 v[84:87], v[222:225], v[152:155], v[84:87]
	v_mfma_f32_16x16x32_bf16 v[132:135], v[204:207], v[156:159], v[132:135]
	v_mfma_f32_16x16x32_bf16 v[136:139], v[210:213], v[156:159], v[136:139]
	v_mfma_f32_16x16x32_bf16 v[140:143], v[214:217], v[156:159], v[140:143]
	v_mfma_f32_16x16x32_bf16 v[80:83], v[222:225], v[156:159], v[80:83]
	s_setprio 0
	ds_read_b128 v[156:159], v221 offset:9216
	ds_read_b128 v[152:155], v221 offset:11264
	ds_read_b128 v[148:151], v221 offset:13312
	ds_read_b128 v[144:147], v221 offset:15360
	s_setprio 1
	s_waitcnt lgkmcnt(4)
	v_mfma_f32_16x16x32_bf16 v[60:63], v[64:67], v[176:179], v[60:63]
	v_mfma_f32_16x16x32_bf16 v[56:59], v[68:71], v[176:179], v[56:59]
	v_mfma_f32_16x16x32_bf16 v[52:55], v[76:79], v[176:179], v[52:55]
	v_mfma_f32_16x16x32_bf16 v[48:51], v[72:75], v[176:179], v[48:51]
	v_mfma_f32_16x16x32_bf16 v[44:47], v[64:67], v[180:183], v[44:47]
	v_mfma_f32_16x16x32_bf16 v[40:43], v[68:71], v[180:183], v[40:43]
	v_mfma_f32_16x16x32_bf16 v[36:39], v[76:79], v[180:183], v[36:39]
	v_mfma_f32_16x16x32_bf16 v[32:35], v[72:75], v[180:183], v[32:35]
	v_mfma_f32_16x16x32_bf16 v[28:31], v[64:67], v[184:187], v[28:31]
	v_mfma_f32_16x16x32_bf16 v[24:27], v[68:71], v[184:187], v[24:27]
	v_mfma_f32_16x16x32_bf16 v[20:23], v[76:79], v[184:187], v[20:23]
	v_mfma_f32_16x16x32_bf16 v[16:19], v[72:75], v[184:187], v[16:19]
	v_mfma_f32_16x16x32_bf16 v[12:15], v[64:67], v[188:191], v[12:15]
	v_mfma_f32_16x16x32_bf16 v[8:11], v[68:71], v[188:191], v[8:11]
	v_mfma_f32_16x16x32_bf16 v[4:7], v[76:79], v[188:191], v[4:7]
	v_mfma_f32_16x16x32_bf16 v[0:3], v[72:75], v[188:191], v[0:3]
	s_setprio 0
	s_waitcnt lgkmcnt(0)
	s_add_u32 s52, s52, 0x80
	s_addc_u32 s53, s53, 0
	s_add_u32 s64, s64, 0x80
	s_addc_u32 s65, s65, 0
	s_add_u32 s4, s4, 0x80
	s_addc_u32 s5, s5, 0
	s_add_i32 s35, s35, 0x10000
	s_cmpk_eq_i32 s4, 0x700
	s_waitcnt vmcnt(0)
	s_barrier
	s_cbranch_scc0 .LBB0_111
	v_readlane_b32 s52, v255, 12
	v_readlane_b32 s53, v255, 13
	v_readlane_b32 s64, v255, 14
	v_readlane_b32 s65, v255, 15
	v_readlane_b32 s30, v255, 16
	v_add_u32_e32 v160, 0x10000, v218
	v_add_u32_e32 v161, 0x10800, v218
	ds_read_b128 v[188:191], v160
	ds_read_b128 v[180:183], v161
	v_add_u32_e32 v160, 0x11000, v218
	v_add_u32_e32 v161, 0x11800, v218
	ds_read_b128 v[184:187], v160
	ds_read_b128 v[176:179], v161
	v_or_b32_e32 v160, 0x18000, v219
	v_add_u32_e32 v164, 0x18800, v219
	v_add_u32_e32 v168, 0x19000, v219
	v_add_u32_e32 v172, 0x19800, v219
	ds_read_b128 v[160:163], v160
	ds_read_b128 v[164:167], v164
	ds_read_b128 v[168:171], v168
	ds_read_b128 v[172:175], v172
	s_ashr_i32 s37, s36, 31
	v_cndmask_b32_e64 v200, 0, 1, s[42:43]
	v_cmp_ne_u32_e64 s[4:5], 1, v200
	s_andn2_b64 vcc, exec, s[42:43]
	s_lshl_b64 s[38:39], s[36:37], 19
	s_cbranch_vccnz .LBB0_114
	s_add_u32 s40, s9, s38
	v_add_u32_e32 v212, 0x8000, v220
	s_addc_u32 s41, s45, s39
	v_add_u32_e32 v215, 0xa000, v220
	v_readfirstlane_b32 s35, v212
	v_lshl_add_u64 v[200:201], s[40:41], 0, v[192:193]
	v_add_u32_e32 v214, 0xc000, v220
	s_mov_b32 m0, s35
	v_readfirstlane_b32 s35, v215
	v_lshl_add_u64 v[204:205], s[40:41], 0, v[194:195]
	v_add_u32_e32 v213, 0xe000, v220
	global_load_lds_dwordx4 v[200:201], off
	s_mov_b32 m0, s35
	v_readfirstlane_b32 s35, v214
	v_lshl_add_u64 v[206:207], s[40:41], 0, v[196:197]
	global_load_lds_dwordx4 v[204:205], off
	s_mov_b32 m0, s35
	v_readfirstlane_b32 s35, v213
	v_lshl_add_u64 v[210:211], s[40:41], 0, v[198:199]
	global_load_lds_dwordx4 v[206:207], off
	s_mov_b32 m0, s35
	s_nop 0
	global_load_lds_dwordx4 v[210:211], off

; #define G_LANE_SETUP() \
;     int tid_ = threadIdx.x; \
;     asm volatile("" : "+v"(tid_));    \
;     const int wid = tid_ >> 6, lane = tid_ & 63, wr = wid >> 2, wc = wid & 3, fr = lane & 15, fq = lane >> 4; \
;     unsigned soff[4];        \
;     _Pragma("unroll") for (int i = 0; i < 4; ++i) { int sR, sC; stage_rc2(wid * 1024 + i * 8192 + lane * 16, sR, sC); soff[i] = (unsigned)(sR * K + sC) * 2u; }
; #define G_STAGE_A(Ap, buf, kt) do { const char* ab_ = (const char*)(Ap) + (size_t)(kt) * 128; \
;       _Pragma("unroll") for (int i = 0; i < 4; ++i) \
;         __builtin_amdgcn_global_load_lds((const unsigned*)(ab_ + soff[i]), (LDSP unsigned*)(G_SA(buf) + wid * 1024 + i * 8192), 16, 0, 0); } while (0)
; #define G_SB0() __builtin_amdgcn_sched_barrier(0)
; template <int EK>
; DI void gemm_stream(const Params& p, int l, const bf16_t* __restrict__ A, const bf16_t* __restrict__ Bt, int M, int N, int K, ldsp_t shm) {
;     ...
;         G_LANE_SETUP();
;         const int aoff = lds_byte2(wr * 128 + fr, fq * 8), boff = lds_byte2(wc * 64 + fr, fq * 8);
;         f32x4 acc[8][4];
; #pragma unroll
;         for (int m = 0; m < 8; ++m)
; #pragma unroll
;             for (int n = 0; n < 4; ++n) acc[m][n] = (f32x4){0.f, 0.f, 0.f, 0.f};
;         const int Ln = L + gridDim.x;
;         const bool has_next = Ln < nwg;
;         int pm2 = pm, pn2 = pn;
;         if (has_next) tile_coords(Ln, nM, nN, pm2, pn2);
;         const bf16_t* Ab2 = A + (size_t)pm2 * 256 * K;
;         const bf16_t* Bb2 = Bt + (size_t)pn2 * 256 * K;
;         bf16x8 Aa[4], Ab_[4], Bk0[4], Bk1[4];
;     ...
;         for (int t = 0; t < nt; ++t) {
;             const int cur = t & 1;
;             G_RDA(Aa, cur, 0, 0); G_RDB(Bk0, cur, 0);
;             if (t + 1 < nt) G_STAGE_B(Bb, cur ^ 1, t + 1);
;             else if (has_next) G_STAGE_B(Bb2, cur ^ 1, 0);
;             G_SB0();
;             if (t > 0) G_MMA(Ab_, Bk1, 1);
;             G_SB0();
;             if (t + 1 < nt) G_STAGE_A(Ab, cur ^ 1, t + 1);
;             else if (has_next) G_STAGE_A(Ab2, cur ^ 1, 0);
;             G_RDA(Ab_, cur, 0, 1);
;             G_MMA(Aa, Bk0, 0); G_SB0();
;             G_RDA(Aa, cur, 1, 0); G_RDB(Bk1, cur, 1);
;             G_MMA(Ab_, Bk0, 1); G_SB0();
;             G_RDA(Ab_, cur, 1, 1);
;             G_MMA(Aa, Bk1, 0); G_SB0();
.LBB0_131:
	v_lshlrev_b32_e32 v0, 4, v160
	v_and_b32_e32 v1, 32, v160
	v_bfe_u32 v161, v160, 2, 4
	v_and_b32_e32 v190, 64, v160
	v_bitop3_b32 v191, v0, v1, 48 bitop3:0x6c
	v_lshrrev_b32_e32 v2, 3, v160
	s_mov_b32 s6, 0x1ffff0
	v_or_b32_e32 v1, v191, v190
	v_and_or_b32 v2, v2, s6, v161
	v_add_u32_e32 v200, 0x2000, v0
	v_lshl_or_b32 v192, v2, 11, v1
	v_lshrrev_b32_e32 v2, 7, v200
	v_and_or_b32 v2, v2, s6, v161
	v_add_u32_e32 v201, 0x4000, v0
	v_add_u32_e32 v221, 0x6000, v0
	v_and_b32_e32 v220, 0xfffffc00, v0
	v_lshl_or_b32 v194, v2, 11, v1
	v_lshrrev_b32_e32 v2, 7, v201
	v_lshrrev_b32_e32 v0, 7, v221
	v_and_or_b32 v2, v2, s6, v161
	v_and_or_b32 v0, v0, s6, v161
	v_lshl_or_b32 v196, v2, 11, v1
	v_lshl_or_b32 v198, v0, 11, v1
	v_lshlrev_b32_e32 v1, 6, v160
	v_lshlrev_b32_e32 v4, 2, v160
	v_and_b32_e32 v0, 48, v160
	v_and_b32_e32 v2, 0x3c0, v1
	v_and_b32_e32 v4, 32, v4
	v_bitop3_b32 v0, v2, v4, v0 bitop3:0x36
	s_movk_i32 s6, 0xc000
	v_and_or_b32 v218, v1, s6, v0
	s_add_u32 s6, s93, s46
	s_addc_u32 s7, s98, s47
	v_add_u32_e32 v34, 0x18000, v220
	v_lshl_add_u64 v[32:33], s[6:7], 0, v[192:193]
	v_readfirstlane_b32 s41, v34
	v_lshlrev_b32_e32 v3, 7, v160
	v_lshl_add_u64 v[32:33], v[32:33], 0, s[0:1]
	s_mov_b32 m0, s41
	v_mov_b32_e32 v195, v193
	v_add_u32_e32 v34, 0x1a000, v220
	v_and_or_b32 v219, v3, s28, v0
	ds_read_b128 v[0:3], v218
	ds_read_b128 v[4:7], v218 offset:2048
	ds_read_b128 v[8:11], v218 offset:4096
	ds_read_b128 v[12:15], v218 offset:6144
	ds_read_b128 v[16:19], v219 offset:32768
	ds_read_b128 v[20:23], v219 offset:34816
	ds_read_b128 v[24:27], v219 offset:36864
	ds_read_b128 v[28:31], v219 offset:38912
	global_load_lds_dwordx4 v[32:33], off
	v_lshl_add_u64 v[32:33], s[6:7], 0, v[194:195]
	v_readfirstlane_b32 s41, v34
	v_lshl_add_u64 v[32:33], v[32:33], 0, s[0:1]
	s_mov_b32 m0, s41
	v_mov_b32_e32 v197, v193
	v_add_u32_e32 v34, 0x1c000, v220
	global_load_lds_dwordx4 v[32:33], off
	v_lshl_add_u64 v[32:33], s[6:7], 0, v[196:197]
	v_readfirstlane_b32 s41, v34
	v_lshl_add_u64 v[32:33], v[32:33], 0, s[0:1]
	s_mov_b32 m0, s41
	v_mov_b32_e32 v199, v193
	v_add_u32_e32 v34, 0x1e000, v220
	global_load_lds_dwordx4 v[32:33], off
	v_lshl_add_u64 v[32:33], s[6:7], 0, v[198:199]
	v_readfirstlane_b32 s6, v34
	v_lshl_add_u64 v[32:33], v[32:33], 0, s[0:1]
	s_mov_b32 m0, s6
	s_nop 0
	global_load_lds_dwordx4 v[32:33], off
	s_add_u32 s6, s26, s50
	s_addc_u32 s7, s27, s51
	v_add_u32_e32 v34, 0x10000, v220
	v_lshl_add_u64 v[32:33], s[6:7], 0, v[192:193]
	v_readfirstlane_b32 s41, v34
	v_lshl_add_u64 v[32:33], v[32:33], 0, s[0:1]
	s_mov_b32 m0, s41
	v_add_u32_e32 v34, 0x12000, v220
	global_load_lds_dwordx4 v[32:33], off
	v_lshl_add_u64 v[32:33], s[6:7], 0, v[194:195]
	v_readfirstlane_b32 s41, v34
	v_lshl_add_u64 v[32:33], v[32:33], 0, s[0:1]
	s_mov_b32 m0, s41
	v_add_u32_e32 v34, 0x14000, v220
	global_load_lds_dwordx4 v[32:33], off
	v_lshl_add_u64 v[32:33], s[6:7], 0, v[196:197]
	v_readfirstlane_b32 s41, v34
	v_lshl_add_u64 v[32:33], v[32:33], 0, s[0:1]
	s_mov_b32 m0, s41
	v_add_u32_e32 v34, 0x16000, v220
	global_load_lds_dwordx4 v[32:33], off
	v_lshl_add_u64 v[32:33], s[6:7], 0, v[198:199]
	v_readfirstlane_b32 s6, v34
	v_lshl_add_u64 v[32:33], v[32:33], 0, s[0:1]
	s_mov_b32 m0, s6
	s_mov_b32 s41, 0x10000
	global_load_lds_dwordx4 v[32:33], off
	ds_read_b128 v[32:35], v218 offset:8192
	ds_read_b128 v[36:39], v218 offset:10240
	ds_read_b128 v[40:43], v218 offset:12288
	ds_read_b128 v[44:47], v218 offset:14336
	s_setprio 1
	s_waitcnt lgkmcnt(0)
	v_mfma_f32_16x16x32_bf16 v[48:51], v[16:19], v[0:3], 0
	v_mfma_f32_16x16x32_bf16 v[52:55], v[20:23], v[0:3], 0
	v_mfma_f32_16x16x32_bf16 v[56:59], v[24:27], v[0:3], 0
	v_mfma_f32_16x16x32_bf16 v[60:63], v[28:31], v[0:3], 0
	v_mfma_f32_16x16x32_bf16 v[162:165], v[16:19], v[4:7], 0
	v_mfma_f32_16x16x32_bf16 v[166:169], v[20:23], v[4:7], 0
	v_mfma_f32_16x16x32_bf16 v[170:173], v[24:27], v[4:7], 0
	v_mfma_f32_16x16x32_bf16 v[174:177], v[28:31], v[4:7], 0
	v_mfma_f32_16x16x32_bf16 v[178:181], v[16:19], v[8:11], 0
	v_mfma_f32_16x16x32_bf16 v[182:185], v[20:23], v[8:11], 0
	v_mfma_f32_16x16x32_bf16 v[186:189], v[24:27], v[8:11], 0
	v_mfma_f32_16x16x32_bf16 v[204:207], v[28:31], v[8:11], 0
	v_mfma_f32_16x16x32_bf16 v[210:213], v[16:19], v[12:15], 0
	v_mfma_f32_16x16x32_bf16 v[214:217], v[20:23], v[12:15], 0
	v_mfma_f32_16x16x32_bf16 v[222:225], v[24:27], v[12:15], 0
	v_mfma_f32_16x16x32_bf16 v[226:229], v[28:31], v[12:15], 0
	s_setprio 0
	ds_read_b128 v[12:15], v218 offset:1024
	ds_read_b128 v[230:233], v218 offset:3072
	ds_read_b128 v[234:237], v218 offset:5120
	ds_read_b128 v[238:241], v218 offset:7168
	ds_read_b128 v[64:67], v219 offset:33792
	ds_read_b128 v[68:71], v219 offset:35840
	ds_read_b128 v[72:75], v219 offset:37888
	ds_read_b128 v[76:79], v219 offset:39936
	s_setprio 1
	v_mfma_f32_16x16x32_bf16 v[140:143], v[16:19], v[32:35], 0
	v_mfma_f32_16x16x32_bf16 v[136:139], v[20:23], v[32:35], 0
	v_mfma_f32_16x16x32_bf16 v[132:135], v[24:27], v[32:35], 0
	v_mfma_f32_16x16x32_bf16 v[128:131], v[28:31], v[32:35], 0
	v_mfma_f32_16x16x32_bf16 v[124:127], v[16:19], v[36:39], 0
	v_mfma_f32_16x16x32_bf16 v[120:123], v[20:23], v[36:39], 0
	v_mfma_f32_16x16x32_bf16 v[116:119], v[24:27], v[36:39], 0
	v_mfma_f32_16x16x32_bf16 v[112:115], v[28:31], v[36:39], 0
	v_mfma_f32_16x16x32_bf16 v[108:111], v[16:19], v[40:43], 0
	v_mfma_f32_16x16x32_bf16 v[104:107], v[20:23], v[40:43], 0
	v_mfma_f32_16x16x32_bf16 v[100:103], v[24:27], v[40:43], 0
	v_mfma_f32_16x16x32_bf16 v[96:99], v[28:31], v[40:43], 0
	v_mfma_f32_16x16x32_bf16 v[92:95], v[16:19], v[44:47], 0
	v_mfma_f32_16x16x32_bf16 v[88:91], v[20:23], v[44:47], 0
	v_mfma_f32_16x16x32_bf16 v[84:87], v[24:27], v[44:47], 0
	v_mfma_f32_16x16x32_bf16 v[80:83], v[28:31], v[44:47], 0
	s_setprio 0
	ds_read_b128 v[156:159], v218 offset:9216
	ds_read_b128 v[152:155], v218 offset:11264
	ds_read_b128 v[148:151], v218 offset:13312
	ds_read_b128 v[144:147], v218 offset:15360
	s_setprio 1
	s_waitcnt lgkmcnt(0)
; #define WAIT_V0() asm volatile("s_waitcnt vmcnt(0)" ::: "memory")
; #define G_STAGE_A(Ap, buf, kt) do { const char* ab_ = (const char*)(Ap) + (size_t)(kt) * 128; \
;       _Pragma("unroll") for (int i = 0; i < 4; ++i) \
;         __builtin_amdgcn_global_load_lds((const unsigned*)(ab_ + soff[i]), (LDSP unsigned*)(G_SA(buf) + wid * 1024 + i * 8192), 16, 0, 0); } while (0)
; #define G_STAGE_B(Bp, buf, kt) do { const char* bb_ = (const char*)(Bp) + (size_t)(kt) * 128; \
;       _Pragma("unroll") for (int i = 0; i < 4; ++i) \
;         __builtin_amdgcn_global_load_lds((const unsigned*)(bb_ + soff[i]), (LDSP unsigned*)(G_SB(buf) + wid * 1024 + i * 8192), 16, 0, 0); } while (0)
; #define G_RDA(AF, buf, ks, mh) do { _Pragma("unroll") for (int m = 0; m < 4; ++m) AF[m] = *(const LDSP bf16x8*)(G_SA(buf) + aoff + ((mh) * 4 + m) * 2048 + (ks) * 1024); } while (0)
; #define G_RDB(BF, buf, ks) do { _Pragma("unroll") for (int n = 0; n < 4; ++n) BF[n] = *(const LDSP bf16x8*)(G_SB(buf) + boff + n * 2048 + (ks) * 1024); } while (0)
; #define G_MMA(AF, BF, mh) do { __builtin_amdgcn_s_setprio(1); \
;             _Pragma("unroll") for (int m = 0; m < 4; ++m) _Pragma("unroll") for (int n = 0; n < 4; ++n) \
;                 acc[(mh) * 4 + m][n] = __builtin_amdgcn_mfma_f32_16x16x32_bf16(BF[n], AF[m], acc[(mh) * 4 + m][n], 0, 0, 0); \
;             __builtin_amdgcn_s_setprio(0); } while (0)
; template <int EK>
; DI void gemm_stream(const Params& p, int l, const bf16_t* __restrict__ A, const bf16_t* __restrict__ Bt, int M, int N, int K, ldsp_t shm) {
;     ...
;         for (int t = 0; t < nt; ++t) {
;             const int cur = t & 1;
;             G_RDA(Aa, cur, 0, 0); G_RDB(Bk0, cur, 0);
;             if (t + 1 < nt) G_STAGE_B(Bb, cur ^ 1, t + 1);
;             else if (has_next) G_STAGE_B(Bb2, cur ^ 1, 0);
;             G_SB0();
;             if (t > 0) G_MMA(Ab_, Bk1, 1);
;             G_SB0();
;             if (t + 1 < nt) G_STAGE_A(Ab, cur ^ 1, t + 1);
;             else if (has_next) G_STAGE_A(Ab2, cur ^ 1, 0);
;             G_RDA(Ab_, cur, 0, 1);
;             G_MMA(Aa, Bk0, 0); G_SB0();
;             G_RDA(Aa, cur, 1, 0); G_RDB(Bk1, cur, 1);
;             G_MMA(Ab_, Bk0, 1); G_SB0();
;             G_RDA(Ab_, cur, 1, 1);
;             G_MMA(Aa, Bk1, 0); G_SB0();
;             asm volatile("s_waitcnt lgkmcnt(0)" ::: "memory");
;             WAIT_V0(); __syncthreads();
	v_mfma_f32_16x16x32_bf16 v[0:3], v[64:67], v[12:15], v[48:51]
	v_mfma_f32_16x16x32_bf16 v[4:7], v[68:71], v[12:15], v[52:55]
	v_mfma_f32_16x16x32_bf16 v[8:11], v[72:75], v[12:15], v[56:59]
	v_mfma_f32_16x16x32_bf16 v[12:15], v[76:79], v[12:15], v[60:63]
	v_mfma_f32_16x16x32_bf16 v[16:19], v[64:67], v[230:233], v[162:165]
	v_mfma_f32_16x16x32_bf16 v[20:23], v[68:71], v[230:233], v[166:169]
	v_mfma_f32_16x16x32_bf16 v[24:27], v[72:75], v[230:233], v[170:173]
	v_mfma_f32_16x16x32_bf16 v[28:31], v[76:79], v[230:233], v[174:177]
	v_mfma_f32_16x16x32_bf16 v[32:35], v[64:67], v[234:237], v[178:181]
	v_mfma_f32_16x16x32_bf16 v[36:39], v[68:71], v[234:237], v[182:185]
	v_mfma_f32_16x16x32_bf16 v[40:43], v[72:75], v[234:237], v[186:189]
	v_mfma_f32_16x16x32_bf16 v[44:47], v[76:79], v[234:237], v[204:207]
	v_mfma_f32_16x16x32_bf16 v[48:51], v[64:67], v[238:241], v[210:213]
	v_mfma_f32_16x16x32_bf16 v[52:55], v[68:71], v[238:241], v[214:217]
	v_mfma_f32_16x16x32_bf16 v[56:59], v[72:75], v[238:241], v[222:225]
	v_mfma_f32_16x16x32_bf16 v[60:63], v[76:79], v[238:241], v[226:229]
	s_setprio 0
	v_lshlrev_b32_e32 v160, 8, v160
	v_lshlrev_b32_e32 v162, 4, v200
	v_lshlrev_b32_e32 v164, 4, v201
	v_lshlrev_b32_e32 v167, 4, v221
	v_and_or_b32 v160, v160, s90, v191
	v_lshlrev_b32_e32 v166, 11, v161
	s_add_u32 s6, s84, s46
	v_and_or_b32 v162, v162, s90, v191
	v_and_or_b32 v164, v164, s90, v191
	v_and_or_b32 v167, v167, s90, v191
	s_waitcnt lgkmcnt(0)
	v_or3_b32 v168, v160, v166, v190
	v_mov_b32_e32 v169, v193
	s_addc_u32 s7, s85, s47
	v_or3_b32 v170, v162, v166, v190
	v_mov_b32_e32 v171, v193
	v_or3_b32 v172, v164, v166, v190
	v_mov_b32_e32 v173, v193
	v_or3_b32 v174, v167, v166, v190
	v_mov_b32_e32 v175, v193
	s_waitcnt vmcnt(0)
	v_writelane_b32 v255, s52, 12
	v_writelane_b32 v255, s53, 13
	v_writelane_b32 v255, s64, 14
	v_writelane_b32 v255, s65, 15
	v_writelane_b32 v255, s30, 16
	s_mov_b64 s[64:65], s[6:7]
	s_add_u32 s6, s24, s50
	s_addc_u32 s7, s25, s51
	s_mov_b64 s[52:53], s[6:7]
	s_mov_b64 s[6:7], 0
	s_waitcnt vmcnt(0)
	v_lshrrev_b32_e32 v164, 6, v252
	v_lshlrev_b32_e32 v164, 10, v164
	s_nop 0
	v_readfirstlane_b32 s30, v164
	v_and_b32_e32 v165, 63, v252
	v_lshlrev_b32_e32 v165, 4, v165
	s_barrier
.LBB0_132:
	s_and_b32 s43, s41, 0x10000
	v_add_u32_e32 v221, s43, v218
	v_or_b32_e32 v226, s43, v219
	s_xor_b32 s43, s43, 0x10000
	s_add_u32 s43, s43, s30
	ds_read_b128 v[176:179], v221
	ds_read_b128 v[180:183], v221 offset:2048
	ds_read_b128 v[184:187], v221 offset:4096
	ds_read_b128 v[188:191], v221 offset:6144
	s_add_u32 m0, s43, 0x8000
	ds_read_b128 v[204:207], v226 offset:32768
	global_load_lds_dwordx4 v168, s[64:65]
	s_add_u32 m0, s43, 0xa000
	ds_read_b128 v[210:213], v226 offset:34816
	global_load_lds_dwordx4 v170, s[64:65]
	s_add_u32 m0, s43, 0xc000
	ds_read_b128 v[214:217], v226 offset:36864
	global_load_lds_dwordx4 v172, s[64:65]
	s_add_u32 m0, s43, 0xe000
	ds_read_b128 v[222:225], v226 offset:38912
	global_load_lds_dwordx4 v174, s[64:65]
	s_setprio 1
	v_mfma_f32_16x16x32_bf16 v[140:143], v[64:67], v[156:159], v[140:143]
	v_mfma_f32_16x16x32_bf16 v[136:139], v[68:71], v[156:159], v[136:139]
	v_mfma_f32_16x16x32_bf16 v[132:135], v[72:75], v[156:159], v[132:135]
	v_mfma_f32_16x16x32_bf16 v[128:131], v[76:79], v[156:159], v[128:131]
	v_mfma_f32_16x16x32_bf16 v[124:127], v[64:67], v[152:155], v[124:127]
	v_mfma_f32_16x16x32_bf16 v[120:123], v[68:71], v[152:155], v[120:123]
	v_mfma_f32_16x16x32_bf16 v[116:119], v[72:75], v[152:155], v[116:119]
	v_mfma_f32_16x16x32_bf16 v[112:115], v[76:79], v[152:155], v[112:115]
	v_mfma_f32_16x16x32_bf16 v[108:111], v[64:67], v[148:151], v[108:111]
	v_mfma_f32_16x16x32_bf16 v[104:107], v[68:71], v[148:151], v[104:107]
	v_mfma_f32_16x16x32_bf16 v[100:103], v[72:75], v[148:151], v[100:103]
	v_mfma_f32_16x16x32_bf16 v[96:99], v[76:79], v[148:151], v[96:99]
	v_mfma_f32_16x16x32_bf16 v[92:95], v[64:67], v[144:147], v[92:95]
	v_mfma_f32_16x16x32_bf16 v[88:91], v[68:71], v[144:147], v[88:91]
	v_mfma_f32_16x16x32_bf16 v[84:87], v[72:75], v[144:147], v[84:87]
	v_mfma_f32_16x16x32_bf16 v[80:83], v[76:79], v[144:147], v[80:83]
	s_setprio 0
	s_add_u32 m0, s43, 0x0
	s_nop 0
	global_load_lds_dwordx4 v168, s[52:53]
	s_add_u32 m0, s43, 0x2000
	s_nop 0
	global_load_lds_dwordx4 v170, s[52:53]
	s_add_u32 m0, s43, 0x4000
	s_nop 0
	global_load_lds_dwordx4 v172, s[52:53]
	s_add_u32 m0, s43, 0x6000
	s_nop 0
	global_load_lds_dwordx4 v174, s[52:53]
	ds_read_b128 v[144:147], v221 offset:8192
	ds_read_b128 v[148:151], v221 offset:10240
	ds_read_b128 v[152:155], v221 offset:12288
	ds_read_b128 v[156:159], v221 offset:14336
	s_setprio 1
	s_waitcnt lgkmcnt(4)
; #define WAIT_V0() asm volatile("s_waitcnt vmcnt(0)" ::: "memory")
; #define G_STAGE_B(Bp, buf, kt) do { const char* bb_ = (const char*)(Bp) + (size_t)(kt) * 128; \
;       _Pragma("unroll") for (int i = 0; i < 4; ++i) \
;         __builtin_amdgcn_global_load_lds((const unsigned*)(bb_ + soff[i]), (LDSP unsigned*)(G_SB(buf) + wid * 1024 + i * 8192), 16, 0, 0); } while (0)
; #define G_RDA(AF, buf, ks, mh) do { _Pragma("unroll") for (int m = 0; m < 4; ++m) AF[m] = *(const LDSP bf16x8*)(G_SA(buf) + aoff + ((mh) * 4 + m) * 2048 + (ks) * 1024); } while (0)
; #define G_RDB(BF, buf, ks) do { _Pragma("unroll") for (int n = 0; n < 4; ++n) BF[n] = *(const LDSP bf16x8*)(G_SB(buf) + boff + n * 2048 + (ks) * 1024); } while (0)
; #define G_MMA(AF, BF, mh) do { __builtin_amdgcn_s_setprio(1); \
;             _Pragma("unroll") for (int m = 0; m < 4; ++m) _Pragma("unroll") for (int n = 0; n < 4; ++n) \
;                 acc[(mh) * 4 + m][n] = __builtin_amdgcn_mfma_f32_16x16x32_bf16(BF[n], AF[m], acc[(mh) * 4 + m][n], 0, 0, 0); \
;             __builtin_amdgcn_s_setprio(0); } while (0)
; #define G_SB0() __builtin_amdgcn_sched_barrier(0)
; template <int EK>
; DI void gemm_stream(const Params& p, int l, const bf16_t* __restrict__ A, const bf16_t* __restrict__ Bt, int M, int N, int K, ldsp_t shm) {
;     ...
;             G_RDA(Aa, cur, 0, 0); G_RDB(Bk0, cur, 0);
;             if (t + 1 < nt) G_STAGE_B(Bb, cur ^ 1, t + 1);
;             else if (has_next) G_STAGE_B(Bb2, cur ^ 1, 0);
;     ...
;             G_MMA(Aa, Bk0, 0); G_SB0();
;             G_RDA(Aa, cur, 1, 0); G_RDB(Bk1, cur, 1);
;             G_MMA(Ab_, Bk0, 1); G_SB0();
;             G_RDA(Ab_, cur, 1, 1);
;             G_MMA(Aa, Bk1, 0); G_SB0();
;             asm volatile("s_waitcnt lgkmcnt(0)" ::: "memory");
;             WAIT_V0(); __syncthreads();
	v_mfma_f32_16x16x32_bf16 v[0:3], v[204:207], v[176:179], v[0:3]
	v_mfma_f32_16x16x32_bf16 v[4:7], v[210:213], v[176:179], v[4:7]
	v_mfma_f32_16x16x32_bf16 v[8:11], v[214:217], v[176:179], v[8:11]
	v_mfma_f32_16x16x32_bf16 v[12:15], v[222:225], v[176:179], v[12:15]
	v_mfma_f32_16x16x32_bf16 v[16:19], v[204:207], v[180:183], v[16:19]
	v_mfma_f32_16x16x32_bf16 v[20:23], v[210:213], v[180:183], v[20:23]
	v_mfma_f32_16x16x32_bf16 v[24:27], v[214:217], v[180:183], v[24:27]
	v_mfma_f32_16x16x32_bf16 v[28:31], v[222:225], v[180:183], v[28:31]
	v_mfma_f32_16x16x32_bf16 v[32:35], v[204:207], v[184:187], v[32:35]
	v_mfma_f32_16x16x32_bf16 v[36:39], v[210:213], v[184:187], v[36:39]
	v_mfma_f32_16x16x32_bf16 v[40:43], v[214:217], v[184:187], v[40:43]
	v_mfma_f32_16x16x32_bf16 v[44:47], v[222:225], v[184:187], v[44:47]
	v_mfma_f32_16x16x32_bf16 v[48:51], v[204:207], v[188:191], v[48:51]
	v_mfma_f32_16x16x32_bf16 v[52:55], v[210:213], v[188:191], v[52:55]
	v_mfma_f32_16x16x32_bf16 v[56:59], v[214:217], v[188:191], v[56:59]
	v_mfma_f32_16x16x32_bf16 v[60:63], v[222:225], v[188:191], v[60:63]
	s_setprio 0
	ds_read_b128 v[176:179], v221 offset:1024
	ds_read_b128 v[180:183], v221 offset:3072
	ds_read_b128 v[184:187], v221 offset:5120
	ds_read_b128 v[188:191], v221 offset:7168
	ds_read_b128 v[64:67], v226 offset:33792
	ds_read_b128 v[68:71], v226 offset:35840
	ds_read_b128 v[72:75], v226 offset:37888
	ds_read_b128 v[76:79], v226 offset:39936
	s_setprio 1
	s_waitcnt lgkmcnt(8)
	v_mfma_f32_16x16x32_bf16 v[140:143], v[204:207], v[144:147], v[140:143]
	v_mfma_f32_16x16x32_bf16 v[136:139], v[210:213], v[144:147], v[136:139]
	v_mfma_f32_16x16x32_bf16 v[132:135], v[214:217], v[144:147], v[132:135]
	v_mfma_f32_16x16x32_bf16 v[128:131], v[222:225], v[144:147], v[128:131]
	v_mfma_f32_16x16x32_bf16 v[124:127], v[204:207], v[148:151], v[124:127]
	v_mfma_f32_16x16x32_bf16 v[120:123], v[210:213], v[148:151], v[120:123]
	v_mfma_f32_16x16x32_bf16 v[116:119], v[214:217], v[148:151], v[116:119]
	v_mfma_f32_16x16x32_bf16 v[112:115], v[222:225], v[148:151], v[112:115]
	v_mfma_f32_16x16x32_bf16 v[108:111], v[204:207], v[152:155], v[108:111]
	v_mfma_f32_16x16x32_bf16 v[104:107], v[210:213], v[152:155], v[104:107]
	v_mfma_f32_16x16x32_bf16 v[100:103], v[214:217], v[152:155], v[100:103]
	v_mfma_f32_16x16x32_bf16 v[96:99], v[222:225], v[152:155], v[96:99]
	v_mfma_f32_16x16x32_bf16 v[92:95], v[204:207], v[156:159], v[92:95]
	v_mfma_f32_16x16x32_bf16 v[88:91], v[210:213], v[156:159], v[88:91]
	v_mfma_f32_16x16x32_bf16 v[84:87], v[214:217], v[156:159], v[84:87]
	v_mfma_f32_16x16x32_bf16 v[80:83], v[222:225], v[156:159], v[80:83]
	s_setprio 0
	ds_read_b128 v[156:159], v221 offset:9216
	ds_read_b128 v[152:155], v221 offset:11264
	ds_read_b128 v[148:151], v221 offset:13312
	ds_read_b128 v[144:147], v221 offset:15360
	s_setprio 1
	s_waitcnt lgkmcnt(4)
	v_mfma_f32_16x16x32_bf16 v[0:3], v[64:67], v[176:179], v[0:3]
	v_mfma_f32_16x16x32_bf16 v[4:7], v[68:71], v[176:179], v[4:7]
	v_mfma_f32_16x16x32_bf16 v[8:11], v[72:75], v[176:179], v[8:11]
	v_mfma_f32_16x16x32_bf16 v[12:15], v[76:79], v[176:179], v[12:15]
	v_mfma_f32_16x16x32_bf16 v[16:19], v[64:67], v[180:183], v[16:19]
	v_mfma_f32_16x16x32_bf16 v[20:23], v[68:71], v[180:183], v[20:23]
	v_mfma_f32_16x16x32_bf16 v[24:27], v[72:75], v[180:183], v[24:27]
	v_mfma_f32_16x16x32_bf16 v[28:31], v[76:79], v[180:183], v[28:31]
	v_mfma_f32_16x16x32_bf16 v[32:35], v[64:67], v[184:187], v[32:35]
	v_mfma_f32_16x16x32_bf16 v[36:39], v[68:71], v[184:187], v[36:39]
	v_mfma_f32_16x16x32_bf16 v[40:43], v[72:75], v[184:187], v[40:43]
	v_mfma_f32_16x16x32_bf16 v[44:47], v[76:79], v[184:187], v[44:47]
	v_mfma_f32_16x16x32_bf16 v[48:51], v[64:67], v[188:191], v[48:51]
	v_mfma_f32_16x16x32_bf16 v[52:55], v[68:71], v[188:191], v[52:55]
	v_mfma_f32_16x16x32_bf16 v[56:59], v[72:75], v[188:191], v[56:59]
	v_mfma_f32_16x16x32_bf16 v[60:63], v[76:79], v[188:191], v[60:63]
	s_setprio 0
	s_waitcnt lgkmcnt(0)
	s_add_u32 s52, s52, 0x80
	s_addc_u32 s53, s53, 0
	s_add_u32 s64, s64, 0x80
	s_addc_u32 s65, s65, 0
	s_add_u32 s6, s6, 0x80
	s_addc_u32 s7, s7, 0
	s_add_i32 s41, s41, 0x10000
	s_cmpk_eq_i32 s6, 0x700
	s_waitcnt vmcnt(0)
	s_barrier
	s_cbranch_scc0 .LBB0_132
	v_readlane_b32 s52, v255, 12
	v_readlane_b32 s53, v255, 13
	v_readlane_b32 s64, v255, 14
	v_readlane_b32 s65, v255, 15
	v_readlane_b32 s30, v255, 16
	v_add_u32_e32 v160, 0x10000, v218
	v_add_u32_e32 v161, 0x10800, v218
	ds_read_b128 v[188:191], v160
	ds_read_b128 v[180:183], v161
	v_add_u32_e32 v160, 0x11000, v218
	v_add_u32_e32 v161, 0x11800, v218
	ds_read_b128 v[184:187], v160
	ds_read_b128 v[176:179], v161
	v_or_b32_e32 v160, 0x18000, v219
	v_add_u32_e32 v164, 0x18800, v219
	v_add_u32_e32 v168, 0x19000, v219
	v_add_u32_e32 v172, 0x19800, v219
	ds_read_b128 v[160:163], v160
	ds_read_b128 v[164:167], v164
	ds_read_b128 v[168:171], v168
	ds_read_b128 v[172:175], v172
	s_ashr_i32 s43, s42, 31
	v_cndmask_b32_e64 v200, 0, 1, s[38:39]
	v_cmp_ne_u32_e64 s[6:7], 1, v200
	s_andn2_b64 vcc, exec, s[38:39]
	s_lshl_b64 s[46:47], s[42:43], 19
	s_cbranch_vccnz .LBB0_135
	s_add_u32 s38, s93, s46
	s_addc_u32 s39, s98, s47
	v_add_u32_e32 v212, 0x8000, v220
	v_lshl_add_u64 v[200:201], s[38:39], 0, v[192:193]
	v_lshl_add_u64 v[204:205], s[38:39], 0, v[194:195]
	v_lshl_add_u64 v[206:207], s[38:39], 0, v[196:197]
	v_lshl_add_u64 v[210:211], s[38:39], 0, v[198:199]
	v_add_u32_e32 v215, 0xa000, v220
	v_readfirstlane_b32 s38, v212
	v_add_u32_e32 v214, 0xc000, v220
	s_mov_b32 m0, s38
	v_readfirstlane_b32 s38, v215
	v_add_u32_e32 v213, 0xe000, v220
	global_load_lds_dwordx4 v[200:201], off
	s_mov_b32 m0, s38
	v_readfirstlane_b32 s38, v214
	global_load_lds_dwordx4 v[204:205], off
	s_mov_b32 m0, s38
	v_readfirstlane_b32 s38, v213
	global_load_lds_dwordx4 v[206:207], off
	s_mov_b32 m0, s38
	s_nop 0
	global_load_lds_dwordx4 v[210:211], off

; #define G_LANE_SETUP() \
;     int tid_ = threadIdx.x; \
;     asm volatile("" : "+v"(tid_));    \
;     const int wid = tid_ >> 6, lane = tid_ & 63, wr = wid >> 2, wc = wid & 3, fr = lane & 15, fq = lane >> 4; \
;     unsigned soff[4];        \
;     _Pragma("unroll") for (int i = 0; i < 4; ++i) { int sR, sC; stage_rc2(wid * 1024 + i * 8192 + lane * 16, sR, sC); soff[i] = (unsigned)(sR * K + sC) * 2u; }
; #define G_STAGE_A(Ap, buf, kt) do { const char* ab_ = (const char*)(Ap) + (size_t)(kt) * 128; \
;       _Pragma("unroll") for (int i = 0; i < 4; ++i) \
;         __builtin_amdgcn_global_load_lds((const unsigned*)(ab_ + soff[i]), (LDSP unsigned*)(G_SA(buf) + wid * 1024 + i * 8192), 16, 0, 0); } while (0)
; #define G_SB0() __builtin_amdgcn_sched_barrier(0)
; template <int EK>
; DI void gemm_stream(const Params& p, int l, const bf16_t* __restrict__ A, const bf16_t* __restrict__ Bt, int M, int N, int K, ldsp_t shm) {
;     ...
;         G_LANE_SETUP();
;         const int aoff = lds_byte2(wr * 128 + fr, fq * 8), boff = lds_byte2(wc * 64 + fr, fq * 8);
;         f32x4 acc[8][4];
; #pragma unroll
;         for (int m = 0; m < 8; ++m)
; #pragma unroll
;             for (int n = 0; n < 4; ++n) acc[m][n] = (f32x4){0.f, 0.f, 0.f, 0.f};
;         const int Ln = L + gridDim.x;
;         const bool has_next = Ln < nwg;
;         int pm2 = pm, pn2 = pn;
;         if (has_next) tile_coords(Ln, nM, nN, pm2, pn2);
;         const bf16_t* Ab2 = A + (size_t)pm2 * 256 * K;
;         const bf16_t* Bb2 = Bt + (size_t)pn2 * 256 * K;
;         bf16x8 Aa[4], Ab_[4], Bk0[4], Bk1[4];
;     ...
;         for (int t = 0; t < nt; ++t) {
;             const int cur = t & 1;
;             G_RDA(Aa, cur, 0, 0); G_RDB(Bk0, cur, 0);
;             if (t + 1 < nt) G_STAGE_B(Bb, cur ^ 1, t + 1);
;             else if (has_next) G_STAGE_B(Bb2, cur ^ 1, 0);
;             G_SB0();
;             if (t > 0) G_MMA(Ab_, Bk1, 1);
;             G_SB0();
;             if (t + 1 < nt) G_STAGE_A(Ab, cur ^ 1, t + 1);
;             else if (has_next) G_STAGE_A(Ab2, cur ^ 1, 0);
;             G_RDA(Ab_, cur, 0, 1);
;             G_MMA(Aa, Bk0, 0); G_SB0();
;             G_RDA(Aa, cur, 1, 0); G_RDB(Bk1, cur, 1);
;             G_MMA(Ab_, Bk0, 1); G_SB0();
;             G_RDA(Ab_, cur, 1, 1);
;             G_MMA(Aa, Bk1, 0); G_SB0();
.LBB0_190:
	v_lshlrev_b32_e32 v0, 4, v160
	v_and_b32_e32 v1, 32, v160
	v_bfe_u32 v161, v160, 2, 4
	v_and_b32_e32 v190, 64, v160
	v_bitop3_b32 v191, v0, v1, 48 bitop3:0x6c
	v_lshrrev_b32_e32 v2, 3, v160
	v_or_b32_e32 v1, v191, v190
	v_and_or_b32 v2, v2, s15, v161
	v_add_u32_e32 v200, 0x2000, v0
	v_lshl_or_b32 v192, v2, 13, v1
	v_lshrrev_b32_e32 v2, 7, v200
	v_and_or_b32 v2, v2, s15, v161
	v_add_u32_e32 v201, 0x4000, v0
	v_add_u32_e32 v221, 0x6000, v0
	v_and_b32_e32 v220, 0xfffffc00, v0
	v_lshl_or_b32 v194, v2, 13, v1
	v_lshrrev_b32_e32 v2, 7, v201
	v_lshrrev_b32_e32 v0, 7, v221
	v_and_or_b32 v2, v2, s15, v161
	v_and_or_b32 v0, v0, s15, v161
	v_lshl_or_b32 v196, v2, 13, v1
	v_lshl_or_b32 v198, v0, 13, v1
	v_lshlrev_b32_e32 v1, 6, v160
	v_lshlrev_b32_e32 v4, 2, v160
	v_and_b32_e32 v0, 48, v160
	v_and_b32_e32 v2, 0x3c0, v1
	v_and_b32_e32 v4, 32, v4
	v_bitop3_b32 v0, v2, v4, v0 bitop3:0x36
	s_movk_i32 s4, 0xc000
	v_and_or_b32 v218, v1, s4, v0
	s_add_u32 s4, s9, s50
	s_addc_u32 s5, s31, s51
	v_add_u32_e32 v34, 0x18000, v220
	v_lshl_add_u64 v[32:33], s[4:5], 0, v[192:193]
	v_readfirstlane_b32 s43, v34
	v_lshlrev_b32_e32 v3, 7, v160
	v_lshl_add_u64 v[32:33], v[32:33], 0, s[0:1]
	s_mov_b32 m0, s43
	v_mov_b32_e32 v195, v193
	v_add_u32_e32 v34, 0x1a000, v220
	v_and_or_b32 v219, v3, s28, v0
	ds_read_b128 v[0:3], v218
	ds_read_b128 v[4:7], v218 offset:2048
	ds_read_b128 v[8:11], v218 offset:4096
	ds_read_b128 v[12:15], v218 offset:6144
	ds_read_b128 v[16:19], v219 offset:32768
	ds_read_b128 v[20:23], v219 offset:34816
	ds_read_b128 v[24:27], v219 offset:36864
	ds_read_b128 v[28:31], v219 offset:38912
	global_load_lds_dwordx4 v[32:33], off
	v_lshl_add_u64 v[32:33], s[4:5], 0, v[194:195]
	v_readfirstlane_b32 s43, v34
	v_lshl_add_u64 v[32:33], v[32:33], 0, s[0:1]
	s_mov_b32 m0, s43
	v_mov_b32_e32 v197, v193
	v_add_u32_e32 v34, 0x1c000, v220
	global_load_lds_dwordx4 v[32:33], off
	v_lshl_add_u64 v[32:33], s[4:5], 0, v[196:197]
	v_readfirstlane_b32 s43, v34
	v_lshl_add_u64 v[32:33], v[32:33], 0, s[0:1]
	s_mov_b32 m0, s43
	v_mov_b32_e32 v199, v193
	v_add_u32_e32 v34, 0x1e000, v220
	global_load_lds_dwordx4 v[32:33], off
	v_lshl_add_u64 v[32:33], s[4:5], 0, v[198:199]
	v_readfirstlane_b32 s4, v34
	v_lshl_add_u64 v[32:33], v[32:33], 0, s[0:1]
	s_mov_b32 m0, s4
	s_nop 0
	global_load_lds_dwordx4 v[32:33], off
	s_add_u32 s4, s12, s6
	s_addc_u32 s5, s13, s7
	v_add_u32_e32 v34, 0x10000, v220
	v_lshl_add_u64 v[32:33], s[4:5], 0, v[192:193]
	v_readfirstlane_b32 s43, v34
	v_lshl_add_u64 v[32:33], v[32:33], 0, s[0:1]
	s_mov_b32 m0, s43
	v_add_u32_e32 v34, 0x12000, v220
	global_load_lds_dwordx4 v[32:33], off
	v_lshl_add_u64 v[32:33], s[4:5], 0, v[194:195]
	v_readfirstlane_b32 s43, v34
	v_lshl_add_u64 v[32:33], v[32:33], 0, s[0:1]
	s_mov_b32 m0, s43
	v_add_u32_e32 v34, 0x14000, v220
	global_load_lds_dwordx4 v[32:33], off
	v_lshl_add_u64 v[32:33], s[4:5], 0, v[196:197]
	v_readfirstlane_b32 s43, v34
	v_lshl_add_u64 v[32:33], v[32:33], 0, s[0:1]
	s_mov_b32 m0, s43
	v_add_u32_e32 v34, 0x16000, v220
	global_load_lds_dwordx4 v[32:33], off
	v_lshl_add_u64 v[32:33], s[4:5], 0, v[198:199]
	v_readfirstlane_b32 s4, v34
	v_lshl_add_u64 v[32:33], v[32:33], 0, s[0:1]
	s_mov_b32 m0, s4
	s_mov_b32 s43, 0x10000
	global_load_lds_dwordx4 v[32:33], off
	ds_read_b128 v[32:35], v218 offset:8192
	ds_read_b128 v[36:39], v218 offset:10240
	ds_read_b128 v[40:43], v218 offset:12288
	ds_read_b128 v[44:47], v218 offset:14336
	s_setprio 1
	s_waitcnt lgkmcnt(0)
	v_mfma_f32_16x16x32_bf16 v[48:51], v[16:19], v[0:3], 0
	v_mfma_f32_16x16x32_bf16 v[52:55], v[20:23], v[0:3], 0
	v_mfma_f32_16x16x32_bf16 v[56:59], v[24:27], v[0:3], 0
	v_mfma_f32_16x16x32_bf16 v[60:63], v[28:31], v[0:3], 0
	v_mfma_f32_16x16x32_bf16 v[162:165], v[16:19], v[4:7], 0
	v_mfma_f32_16x16x32_bf16 v[166:169], v[20:23], v[4:7], 0
	v_mfma_f32_16x16x32_bf16 v[170:173], v[24:27], v[4:7], 0
	v_mfma_f32_16x16x32_bf16 v[174:177], v[28:31], v[4:7], 0
	v_mfma_f32_16x16x32_bf16 v[178:181], v[16:19], v[8:11], 0
	v_mfma_f32_16x16x32_bf16 v[182:185], v[20:23], v[8:11], 0
	v_mfma_f32_16x16x32_bf16 v[186:189], v[24:27], v[8:11], 0
	v_mfma_f32_16x16x32_bf16 v[204:207], v[28:31], v[8:11], 0
	v_mfma_f32_16x16x32_bf16 v[210:213], v[16:19], v[12:15], 0
	v_mfma_f32_16x16x32_bf16 v[214:217], v[20:23], v[12:15], 0
	v_mfma_f32_16x16x32_bf16 v[222:225], v[24:27], v[12:15], 0
	v_mfma_f32_16x16x32_bf16 v[226:229], v[28:31], v[12:15], 0
	s_setprio 0
	ds_read_b128 v[12:15], v218 offset:1024
	ds_read_b128 v[230:233], v218 offset:3072
	ds_read_b128 v[234:237], v218 offset:5120
	ds_read_b128 v[238:241], v218 offset:7168
	ds_read_b128 v[64:67], v219 offset:33792
	ds_read_b128 v[68:71], v219 offset:35840
	ds_read_b128 v[72:75], v219 offset:37888
	ds_read_b128 v[76:79], v219 offset:39936
	s_setprio 1
	v_mfma_f32_16x16x32_bf16 v[140:143], v[16:19], v[32:35], 0
	v_mfma_f32_16x16x32_bf16 v[136:139], v[20:23], v[32:35], 0
	v_mfma_f32_16x16x32_bf16 v[132:135], v[24:27], v[32:35], 0
	v_mfma_f32_16x16x32_bf16 v[128:131], v[28:31], v[32:35], 0
	v_mfma_f32_16x16x32_bf16 v[124:127], v[16:19], v[36:39], 0
	v_mfma_f32_16x16x32_bf16 v[120:123], v[20:23], v[36:39], 0
	v_mfma_f32_16x16x32_bf16 v[116:119], v[24:27], v[36:39], 0
	v_mfma_f32_16x16x32_bf16 v[112:115], v[28:31], v[36:39], 0
	v_mfma_f32_16x16x32_bf16 v[108:111], v[16:19], v[40:43], 0
	v_mfma_f32_16x16x32_bf16 v[104:107], v[20:23], v[40:43], 0
	v_mfma_f32_16x16x32_bf16 v[100:103], v[24:27], v[40:43], 0
	v_mfma_f32_16x16x32_bf16 v[96:99], v[28:31], v[40:43], 0
	v_mfma_f32_16x16x32_bf16 v[92:95], v[16:19], v[44:47], 0
	v_mfma_f32_16x16x32_bf16 v[88:91], v[20:23], v[44:47], 0
	v_mfma_f32_16x16x32_bf16 v[84:87], v[24:27], v[44:47], 0
	v_mfma_f32_16x16x32_bf16 v[80:83], v[28:31], v[44:47], 0
	s_setprio 0
	ds_read_b128 v[156:159], v218 offset:9216
	ds_read_b128 v[152:155], v218 offset:11264
	ds_read_b128 v[148:151], v218 offset:13312
	ds_read_b128 v[144:147], v218 offset:15360
	s_setprio 1
	s_waitcnt lgkmcnt(0)
; #define WAIT_V0() asm volatile("s_waitcnt vmcnt(0)" ::: "memory")
; #define G_STAGE_A(Ap, buf, kt) do { const char* ab_ = (const char*)(Ap) + (size_t)(kt) * 128; \
;       _Pragma("unroll") for (int i = 0; i < 4; ++i) \
;         __builtin_amdgcn_global_load_lds((const unsigned*)(ab_ + soff[i]), (LDSP unsigned*)(G_SA(buf) + wid * 1024 + i * 8192), 16, 0, 0); } while (0)
; #define G_STAGE_B(Bp, buf, kt) do { const char* bb_ = (const char*)(Bp) + (size_t)(kt) * 128; \
;       _Pragma("unroll") for (int i = 0; i < 4; ++i) \
;         __builtin_amdgcn_global_load_lds((const unsigned*)(bb_ + soff[i]), (LDSP unsigned*)(G_SB(buf) + wid * 1024 + i * 8192), 16, 0, 0); } while (0)
; #define G_RDA(AF, buf, ks, mh) do { _Pragma("unroll") for (int m = 0; m < 4; ++m) AF[m] = *(const LDSP bf16x8*)(G_SA(buf) + aoff + ((mh) * 4 + m) * 2048 + (ks) * 1024); } while (0)
; #define G_RDB(BF, buf, ks) do { _Pragma("unroll") for (int n = 0; n < 4; ++n) BF[n] = *(const LDSP bf16x8*)(G_SB(buf) + boff + n * 2048 + (ks) * 1024); } while (0)
; #define G_MMA(AF, BF, mh) do { __builtin_amdgcn_s_setprio(1); \
;             _Pragma("unroll") for (int m = 0; m < 4; ++m) _Pragma("unroll") for (int n = 0; n < 4; ++n) \
;                 acc[(mh) * 4 + m][n] = __builtin_amdgcn_mfma_f32_16x16x32_bf16(BF[n], AF[m], acc[(mh) * 4 + m][n], 0, 0, 0); \
;             __builtin_amdgcn_s_setprio(0); } while (0)
; template <int EK>
; DI void gemm_stream(const Params& p, int l, const bf16_t* __restrict__ A, const bf16_t* __restrict__ Bt, int M, int N, int K, ldsp_t shm) {
;     ...
;         for (int t = 0; t < nt; ++t) {
;             const int cur = t & 1;
;             G_RDA(Aa, cur, 0, 0); G_RDB(Bk0, cur, 0);
;             if (t + 1 < nt) G_STAGE_B(Bb, cur ^ 1, t + 1);
;             else if (has_next) G_STAGE_B(Bb2, cur ^ 1, 0);
;             G_SB0();
;             if (t > 0) G_MMA(Ab_, Bk1, 1);
;             G_SB0();
;             if (t + 1 < nt) G_STAGE_A(Ab, cur ^ 1, t + 1);
;             else if (has_next) G_STAGE_A(Ab2, cur ^ 1, 0);
;             G_RDA(Ab_, cur, 0, 1);
;             G_MMA(Aa, Bk0, 0); G_SB0();
;             G_RDA(Aa, cur, 1, 0); G_RDB(Bk1, cur, 1);
;             G_MMA(Ab_, Bk0, 1); G_SB0();
;             G_RDA(Ab_, cur, 1, 1);
;             G_MMA(Aa, Bk1, 0); G_SB0();
;             asm volatile("s_waitcnt lgkmcnt(0)" ::: "memory");
;             WAIT_V0(); __syncthreads();
	v_mfma_f32_16x16x32_bf16 v[0:3], v[64:67], v[12:15], v[48:51]
	v_mfma_f32_16x16x32_bf16 v[4:7], v[68:71], v[12:15], v[52:55]
	v_mfma_f32_16x16x32_bf16 v[8:11], v[72:75], v[12:15], v[56:59]
	v_mfma_f32_16x16x32_bf16 v[12:15], v[76:79], v[12:15], v[60:63]
	v_mfma_f32_16x16x32_bf16 v[16:19], v[64:67], v[230:233], v[162:165]
	v_mfma_f32_16x16x32_bf16 v[20:23], v[68:71], v[230:233], v[166:169]
	v_mfma_f32_16x16x32_bf16 v[24:27], v[72:75], v[230:233], v[170:173]
	v_mfma_f32_16x16x32_bf16 v[28:31], v[76:79], v[230:233], v[174:177]
	v_mfma_f32_16x16x32_bf16 v[32:35], v[64:67], v[234:237], v[178:181]
	v_mfma_f32_16x16x32_bf16 v[36:39], v[68:71], v[234:237], v[182:185]
	v_mfma_f32_16x16x32_bf16 v[40:43], v[72:75], v[234:237], v[186:189]
	v_mfma_f32_16x16x32_bf16 v[44:47], v[76:79], v[234:237], v[204:207]
	v_mfma_f32_16x16x32_bf16 v[48:51], v[64:67], v[238:241], v[210:213]
	v_mfma_f32_16x16x32_bf16 v[52:55], v[68:71], v[238:241], v[214:217]
	v_mfma_f32_16x16x32_bf16 v[56:59], v[72:75], v[238:241], v[222:225]
	v_mfma_f32_16x16x32_bf16 v[60:63], v[76:79], v[238:241], v[226:229]
	s_setprio 0
	v_lshlrev_b32_e32 v160, 10, v160
	s_mov_b32 s47, 0xfffe0000
	v_lshlrev_b32_e32 v162, 6, v200
	v_lshlrev_b32_e32 v164, 6, v201
	v_lshlrev_b32_e32 v167, 6, v221
	v_and_or_b32 v160, v160, s47, v191
	v_lshlrev_b32_e32 v166, 13, v161
	s_add_u32 s4, s84, s50
	v_and_or_b32 v162, v162, s47, v191
	v_and_or_b32 v164, v164, s47, v191
	v_and_or_b32 v167, v167, s47, v191
	s_waitcnt lgkmcnt(0)
	v_or3_b32 v168, v160, v166, v190
	v_mov_b32_e32 v169, v193
	s_addc_u32 s5, s85, s51
	v_or3_b32 v170, v162, v166, v190
	v_mov_b32_e32 v171, v193
	v_or3_b32 v172, v164, v166, v190
	v_mov_b32_e32 v173, v193
	v_or3_b32 v174, v167, v166, v190
	v_mov_b32_e32 v175, v193
	s_waitcnt vmcnt(0)
	v_writelane_b32 v255, s52, 12
	v_writelane_b32 v255, s53, 13
	v_writelane_b32 v255, s64, 14
	v_writelane_b32 v255, s65, 15
	v_writelane_b32 v255, s30, 16
	s_mov_b64 s[64:65], s[4:5]
	s_add_u32 s4, s8, s6
	s_addc_u32 s5, s14, s7
	s_mov_b64 s[52:53], s[4:5]
	s_mov_b64 s[4:5], 0
	s_waitcnt vmcnt(0)
	v_lshrrev_b32_e32 v164, 6, v252
	v_lshlrev_b32_e32 v164, 10, v164
	s_nop 0
	v_readfirstlane_b32 s30, v164
	v_and_b32_e32 v165, 63, v252
	v_lshlrev_b32_e32 v165, 4, v165
	s_barrier
.LBB0_191:
	s_and_b32 s6, s43, 0x10000
	v_add_u32_e32 v221, s6, v218
	v_or_b32_e32 v226, s6, v219
	s_xor_b32 s6, s6, 0x10000
	s_add_u32 s6, s6, s30
	ds_read_b128 v[176:179], v221
	ds_read_b128 v[180:183], v221 offset:2048
	ds_read_b128 v[184:187], v221 offset:4096
	ds_read_b128 v[188:191], v221 offset:6144
	s_add_u32 m0, s6, 0x8000
	ds_read_b128 v[204:207], v226 offset:32768
	global_load_lds_dwordx4 v168, s[64:65]
	s_add_u32 m0, s6, 0xa000
	ds_read_b128 v[210:213], v226 offset:34816
	global_load_lds_dwordx4 v170, s[64:65]
	s_add_u32 m0, s6, 0xc000
	ds_read_b128 v[214:217], v226 offset:36864
	global_load_lds_dwordx4 v172, s[64:65]
	s_add_u32 m0, s6, 0xe000
	ds_read_b128 v[222:225], v226 offset:38912
	global_load_lds_dwordx4 v174, s[64:65]
	s_setprio 1
	v_mfma_f32_16x16x32_bf16 v[140:143], v[64:67], v[156:159], v[140:143]
	v_mfma_f32_16x16x32_bf16 v[136:139], v[68:71], v[156:159], v[136:139]
	v_mfma_f32_16x16x32_bf16 v[132:135], v[72:75], v[156:159], v[132:135]
	v_mfma_f32_16x16x32_bf16 v[128:131], v[76:79], v[156:159], v[128:131]
	v_mfma_f32_16x16x32_bf16 v[124:127], v[64:67], v[152:155], v[124:127]
	v_mfma_f32_16x16x32_bf16 v[120:123], v[68:71], v[152:155], v[120:123]
	v_mfma_f32_16x16x32_bf16 v[116:119], v[72:75], v[152:155], v[116:119]
	v_mfma_f32_16x16x32_bf16 v[112:115], v[76:79], v[152:155], v[112:115]
	v_mfma_f32_16x16x32_bf16 v[108:111], v[64:67], v[148:151], v[108:111]
	v_mfma_f32_16x16x32_bf16 v[104:107], v[68:71], v[148:151], v[104:107]
	v_mfma_f32_16x16x32_bf16 v[100:103], v[72:75], v[148:151], v[100:103]
	v_mfma_f32_16x16x32_bf16 v[96:99], v[76:79], v[148:151], v[96:99]
	v_mfma_f32_16x16x32_bf16 v[92:95], v[64:67], v[144:147], v[92:95]
	v_mfma_f32_16x16x32_bf16 v[88:91], v[68:71], v[144:147], v[88:91]
	v_mfma_f32_16x16x32_bf16 v[84:87], v[72:75], v[144:147], v[84:87]
	v_mfma_f32_16x16x32_bf16 v[80:83], v[76:79], v[144:147], v[80:83]
	s_setprio 0
	s_add_u32 m0, s6, 0x0
	s_nop 0
	global_load_lds_dwordx4 v168, s[52:53]
	s_add_u32 m0, s6, 0x2000
	s_nop 0
	global_load_lds_dwordx4 v170, s[52:53]
	s_add_u32 m0, s6, 0x4000
	s_nop 0
	global_load_lds_dwordx4 v172, s[52:53]
	s_add_u32 m0, s6, 0x6000
	s_nop 0
	global_load_lds_dwordx4 v174, s[52:53]
	ds_read_b128 v[144:147], v221 offset:8192
	ds_read_b128 v[148:151], v221 offset:10240
	ds_read_b128 v[152:155], v221 offset:12288
	ds_read_b128 v[156:159], v221 offset:14336
	s_setprio 1
	s_waitcnt lgkmcnt(4)
; #define WAIT_V0() asm volatile("s_waitcnt vmcnt(0)" ::: "memory")
; #define G_STAGE_B(Bp, buf, kt) do { const char* bb_ = (const char*)(Bp) + (size_t)(kt) * 128; \
;       _Pragma("unroll") for (int i = 0; i < 4; ++i) \
;         __builtin_amdgcn_global_load_lds((const unsigned*)(bb_ + soff[i]), (LDSP unsigned*)(G_SB(buf) + wid * 1024 + i * 8192), 16, 0, 0); } while (0)
; #define G_RDA(AF, buf, ks, mh) do { _Pragma("unroll") for (int m = 0; m < 4; ++m) AF[m] = *(const LDSP bf16x8*)(G_SA(buf) + aoff + ((mh) * 4 + m) * 2048 + (ks) * 1024); } while (0)
; #define G_RDB(BF, buf, ks) do { _Pragma("unroll") for (int n = 0; n < 4; ++n) BF[n] = *(const LDSP bf16x8*)(G_SB(buf) + boff + n * 2048 + (ks) * 1024); } while (0)
; #define G_MMA(AF, BF, mh) do { __builtin_amdgcn_s_setprio(1); \
;             _Pragma("unroll") for (int m = 0; m < 4; ++m) _Pragma("unroll") for (int n = 0; n < 4; ++n) \
;                 acc[(mh) * 4 + m][n] = __builtin_amdgcn_mfma_f32_16x16x32_bf16(BF[n], AF[m], acc[(mh) * 4 + m][n], 0, 0, 0); \
;             __builtin_amdgcn_s_setprio(0); } while (0)
; #define G_SB0() __builtin_amdgcn_sched_barrier(0)
; template <int EK>
; DI void gemm_stream(const Params& p, int l, const bf16_t* __restrict__ A, const bf16_t* __restrict__ Bt, int M, int N, int K, ldsp_t shm) {
;     ...
;             G_RDA(Aa, cur, 0, 0); G_RDB(Bk0, cur, 0);
;             if (t + 1 < nt) G_STAGE_B(Bb, cur ^ 1, t + 1);
;             else if (has_next) G_STAGE_B(Bb2, cur ^ 1, 0);
;     ...
;             G_MMA(Aa, Bk0, 0); G_SB0();
;             G_RDA(Aa, cur, 1, 0); G_RDB(Bk1, cur, 1);
;             G_MMA(Ab_, Bk0, 1); G_SB0();
;             G_RDA(Ab_, cur, 1, 1);
;             G_MMA(Aa, Bk1, 0); G_SB0();
;             asm volatile("s_waitcnt lgkmcnt(0)" ::: "memory");
;             WAIT_V0(); __syncthreads();
	v_mfma_f32_16x16x32_bf16 v[0:3], v[204:207], v[176:179], v[0:3]
	v_mfma_f32_16x16x32_bf16 v[4:7], v[210:213], v[176:179], v[4:7]
	v_mfma_f32_16x16x32_bf16 v[8:11], v[214:217], v[176:179], v[8:11]
	v_mfma_f32_16x16x32_bf16 v[12:15], v[222:225], v[176:179], v[12:15]
	v_mfma_f32_16x16x32_bf16 v[16:19], v[204:207], v[180:183], v[16:19]
	v_mfma_f32_16x16x32_bf16 v[20:23], v[210:213], v[180:183], v[20:23]
	v_mfma_f32_16x16x32_bf16 v[24:27], v[214:217], v[180:183], v[24:27]
	v_mfma_f32_16x16x32_bf16 v[28:31], v[222:225], v[180:183], v[28:31]
	v_mfma_f32_16x16x32_bf16 v[32:35], v[204:207], v[184:187], v[32:35]
	v_mfma_f32_16x16x32_bf16 v[36:39], v[210:213], v[184:187], v[36:39]
	v_mfma_f32_16x16x32_bf16 v[40:43], v[214:217], v[184:187], v[40:43]
	v_mfma_f32_16x16x32_bf16 v[44:47], v[222:225], v[184:187], v[44:47]
	v_mfma_f32_16x16x32_bf16 v[48:51], v[204:207], v[188:191], v[48:51]
	v_mfma_f32_16x16x32_bf16 v[52:55], v[210:213], v[188:191], v[52:55]
	v_mfma_f32_16x16x32_bf16 v[56:59], v[214:217], v[188:191], v[56:59]
	v_mfma_f32_16x16x32_bf16 v[60:63], v[222:225], v[188:191], v[60:63]
	s_setprio 0
	ds_read_b128 v[176:179], v221 offset:1024
	ds_read_b128 v[180:183], v221 offset:3072
	ds_read_b128 v[184:187], v221 offset:5120
	ds_read_b128 v[188:191], v221 offset:7168
	ds_read_b128 v[64:67], v226 offset:33792
	ds_read_b128 v[68:71], v226 offset:35840
	ds_read_b128 v[72:75], v226 offset:37888
	ds_read_b128 v[76:79], v226 offset:39936
	s_setprio 1
	s_waitcnt lgkmcnt(8)
	v_mfma_f32_16x16x32_bf16 v[140:143], v[204:207], v[144:147], v[140:143]
	v_mfma_f32_16x16x32_bf16 v[136:139], v[210:213], v[144:147], v[136:139]
	v_mfma_f32_16x16x32_bf16 v[132:135], v[214:217], v[144:147], v[132:135]
	v_mfma_f32_16x16x32_bf16 v[128:131], v[222:225], v[144:147], v[128:131]
	v_mfma_f32_16x16x32_bf16 v[124:127], v[204:207], v[148:151], v[124:127]
	v_mfma_f32_16x16x32_bf16 v[120:123], v[210:213], v[148:151], v[120:123]
	v_mfma_f32_16x16x32_bf16 v[116:119], v[214:217], v[148:151], v[116:119]
	v_mfma_f32_16x16x32_bf16 v[112:115], v[222:225], v[148:151], v[112:115]
	v_mfma_f32_16x16x32_bf16 v[108:111], v[204:207], v[152:155], v[108:111]
	v_mfma_f32_16x16x32_bf16 v[104:107], v[210:213], v[152:155], v[104:107]
	v_mfma_f32_16x16x32_bf16 v[100:103], v[214:217], v[152:155], v[100:103]
	v_mfma_f32_16x16x32_bf16 v[96:99], v[222:225], v[152:155], v[96:99]
	v_mfma_f32_16x16x32_bf16 v[92:95], v[204:207], v[156:159], v[92:95]
	v_mfma_f32_16x16x32_bf16 v[88:91], v[210:213], v[156:159], v[88:91]
	v_mfma_f32_16x16x32_bf16 v[84:87], v[214:217], v[156:159], v[84:87]
	v_mfma_f32_16x16x32_bf16 v[80:83], v[222:225], v[156:159], v[80:83]
	s_setprio 0
	ds_read_b128 v[156:159], v221 offset:9216
	ds_read_b128 v[152:155], v221 offset:11264
	ds_read_b128 v[148:151], v221 offset:13312
	ds_read_b128 v[144:147], v221 offset:15360
	s_setprio 1
	s_waitcnt lgkmcnt(4)
	v_mfma_f32_16x16x32_bf16 v[0:3], v[64:67], v[176:179], v[0:3]
	v_mfma_f32_16x16x32_bf16 v[4:7], v[68:71], v[176:179], v[4:7]
	v_mfma_f32_16x16x32_bf16 v[8:11], v[72:75], v[176:179], v[8:11]
	v_mfma_f32_16x16x32_bf16 v[12:15], v[76:79], v[176:179], v[12:15]
	v_mfma_f32_16x16x32_bf16 v[16:19], v[64:67], v[180:183], v[16:19]
	v_mfma_f32_16x16x32_bf16 v[20:23], v[68:71], v[180:183], v[20:23]
	v_mfma_f32_16x16x32_bf16 v[24:27], v[72:75], v[180:183], v[24:27]
	v_mfma_f32_16x16x32_bf16 v[28:31], v[76:79], v[180:183], v[28:31]
	v_mfma_f32_16x16x32_bf16 v[32:35], v[64:67], v[184:187], v[32:35]
	v_mfma_f32_16x16x32_bf16 v[36:39], v[68:71], v[184:187], v[36:39]
	v_mfma_f32_16x16x32_bf16 v[40:43], v[72:75], v[184:187], v[40:43]
	v_mfma_f32_16x16x32_bf16 v[44:47], v[76:79], v[184:187], v[44:47]
	v_mfma_f32_16x16x32_bf16 v[48:51], v[64:67], v[188:191], v[48:51]
	v_mfma_f32_16x16x32_bf16 v[52:55], v[68:71], v[188:191], v[52:55]
	v_mfma_f32_16x16x32_bf16 v[56:59], v[72:75], v[188:191], v[56:59]
	v_mfma_f32_16x16x32_bf16 v[60:63], v[76:79], v[188:191], v[60:63]
	s_setprio 0
	s_waitcnt lgkmcnt(0)
	s_add_u32 s52, s52, 0x80
	s_addc_u32 s53, s53, 0
	s_add_u32 s64, s64, 0x80
	s_addc_u32 s65, s65, 0
	s_add_u32 s4, s4, 0x80
	s_addc_u32 s5, s5, 0
	s_add_i32 s43, s43, 0x10000
	s_cmpk_eq_i32 s4, 0x1f00
	s_waitcnt vmcnt(0)
	s_barrier
	s_cbranch_scc0 .LBB0_191
	v_readlane_b32 s52, v255, 12
	v_readlane_b32 s53, v255, 13
	v_readlane_b32 s64, v255, 14
	v_readlane_b32 s65, v255, 15
	v_readlane_b32 s30, v255, 16
	v_add_u32_e32 v160, 0x10000, v218
	v_add_u32_e32 v161, 0x10800, v218
	ds_read_b128 v[188:191], v160
	ds_read_b128 v[180:183], v161
	v_add_u32_e32 v160, 0x11000, v218
	v_add_u32_e32 v161, 0x11800, v218
	ds_read_b128 v[184:187], v160
	ds_read_b128 v[176:179], v161
	v_or_b32_e32 v160, 0x18000, v219
	v_add_u32_e32 v164, 0x18800, v219
	v_add_u32_e32 v168, 0x19000, v219
	v_add_u32_e32 v172, 0x19800, v219
	ds_read_b128 v[160:163], v160
	ds_read_b128 v[164:167], v164
	ds_read_b128 v[168:171], v168
	ds_read_b128 v[172:175], v172
	s_ashr_i32 s47, s46, 31
	v_cndmask_b32_e64 v200, 0, 1, s[34:35]
	v_cmp_ne_u32_e64 s[4:5], 1, v200
	s_andn2_b64 vcc, exec, s[34:35]
	s_lshl_b64 s[50:51], s[46:47], 21
	s_cbranch_vccnz .LBB0_194
	s_add_u32 s6, s9, s50
	s_addc_u32 s7, s31, s51
	v_add_u32_e32 v212, 0x8000, v220
	v_lshl_add_u64 v[200:201], s[6:7], 0, v[192:193]
	v_lshl_add_u64 v[204:205], s[6:7], 0, v[194:195]
	v_lshl_add_u64 v[206:207], s[6:7], 0, v[196:197]
	v_lshl_add_u64 v[210:211], s[6:7], 0, v[198:199]
	v_add_u32_e32 v215, 0xa000, v220
	v_readfirstlane_b32 s6, v212
	v_add_u32_e32 v214, 0xc000, v220
	s_mov_b32 m0, s6
	v_readfirstlane_b32 s6, v215
	v_add_u32_e32 v213, 0xe000, v220
	global_load_lds_dwordx4 v[200:201], off
	s_mov_b32 m0, s6
	v_readfirstlane_b32 s6, v214
	global_load_lds_dwordx4 v[204:205], off
	s_mov_b32 m0, s6
	v_readfirstlane_b32 s6, v213
	global_load_lds_dwordx4 v[206:207], off
	s_mov_b32 m0, s6
	s_nop 0
	global_load_lds_dwordx4 v[210:211], off

; #define G_LANE_SETUP() \
;     int tid_ = threadIdx.x; \
;     asm volatile("" : "+v"(tid_));    \
;     const int wid = tid_ >> 6, lane = tid_ & 63, wr = wid >> 2, wc = wid & 3, fr = lane & 15, fq = lane >> 4; \
;     unsigned soff[4];        \
;     _Pragma("unroll") for (int i = 0; i < 4; ++i) { int sR, sC; stage_rc2(wid * 1024 + i * 8192 + lane * 16, sR, sC); soff[i] = (unsigned)(sR * K + sC) * 2u; }
; #define G_STAGE_A(Ap, buf, kt) do { const char* ab_ = (const char*)(Ap) + (size_t)(kt) * 128; \
;       _Pragma("unroll") for (int i = 0; i < 4; ++i) \
;         __builtin_amdgcn_global_load_lds((const unsigned*)(ab_ + soff[i]), (LDSP unsigned*)(G_SA(buf) + wid * 1024 + i * 8192), 16, 0, 0); } while (0)
; #define G_SB0() __builtin_amdgcn_sched_barrier(0)
; template <int EK>
; DI void gemm_stream(const Params& p, int l, const bf16_t* __restrict__ A, const bf16_t* __restrict__ Bt, int M, int N, int K, ldsp_t shm) {
;     ...
;         G_LANE_SETUP();
;         const int aoff = lds_byte2(wr * 128 + fr, fq * 8), boff = lds_byte2(wc * 64 + fr, fq * 8);
;         f32x4 acc[8][4];
; #pragma unroll
;         for (int m = 0; m < 8; ++m)
; #pragma unroll
;             for (int n = 0; n < 4; ++n) acc[m][n] = (f32x4){0.f, 0.f, 0.f, 0.f};
;         const int Ln = L + gridDim.x;
;         const bool has_next = Ln < nwg;
;         int pm2 = pm, pn2 = pn;
;         if (has_next) tile_coords(Ln, nM, nN, pm2, pn2);
;         const bf16_t* Ab2 = A + (size_t)pm2 * 256 * K;
;         const bf16_t* Bb2 = Bt + (size_t)pn2 * 256 * K;
;         bf16x8 Aa[4], Ab_[4], Bk0[4], Bk1[4];
;     ...
;         for (int t = 0; t < nt; ++t) {
;             const int cur = t & 1;
;             G_RDA(Aa, cur, 0, 0); G_RDB(Bk0, cur, 0);
;             if (t + 1 < nt) G_STAGE_B(Bb, cur ^ 1, t + 1);
;             else if (has_next) G_STAGE_B(Bb2, cur ^ 1, 0);
;             G_SB0();
;             if (t > 0) G_MMA(Ab_, Bk1, 1);
;             G_SB0();
;             if (t + 1 < nt) G_STAGE_A(Ab, cur ^ 1, t + 1);
;             else if (has_next) G_STAGE_A(Ab2, cur ^ 1, 0);
;             G_RDA(Ab_, cur, 0, 1);
;             G_MMA(Aa, Bk0, 0); G_SB0();
;             G_RDA(Aa, cur, 1, 0); G_RDB(Bk1, cur, 1);
;             G_MMA(Ab_, Bk0, 1); G_SB0();
;             G_RDA(Ab_, cur, 1, 1);
;             G_MMA(Aa, Bk1, 0); G_SB0();
.LBB0_263:
	v_lshlrev_b32_e32 v0, 4, v160
	v_and_b32_e32 v1, 32, v160
	v_bfe_u32 v161, v160, 2, 4
	v_and_b32_e32 v190, 64, v160
	v_bitop3_b32 v191, v0, v1, 48 bitop3:0x6c
	v_lshrrev_b32_e32 v2, 3, v160
	v_or_b32_e32 v1, v191, v190
	v_and_or_b32 v2, v2, s86, v161
	v_add_u32_e32 v200, 0x2000, v0
	v_lshl_or_b32 v192, v2, 11, v1
	v_lshrrev_b32_e32 v2, 7, v200
	v_and_or_b32 v2, v2, s86, v161
	v_add_u32_e32 v201, 0x4000, v0
	v_add_u32_e32 v204, 0x6000, v0
	v_and_b32_e32 v220, 0xfffffc00, v0
	v_lshl_or_b32 v194, v2, 11, v1
	v_lshrrev_b32_e32 v2, 7, v201
	v_lshrrev_b32_e32 v0, 7, v204
	v_and_or_b32 v2, v2, s86, v161
	v_and_or_b32 v0, v0, s86, v161
	v_lshl_or_b32 v196, v2, 11, v1
	v_lshl_or_b32 v198, v0, 11, v1
	v_lshlrev_b32_e32 v1, 6, v160
	v_lshlrev_b32_e32 v4, 2, v160
	v_and_b32_e32 v0, 48, v160
	v_and_b32_e32 v2, 0x3c0, v1
	v_and_b32_e32 v4, 32, v4
	v_bitop3_b32 v0, v2, v4, v0 bitop3:0x36
	s_movk_i32 s4, 0xc000
	v_and_or_b32 v218, v1, s4, v0
	s_add_u32 s4, s14, s46
	s_addc_u32 s5, s15, s47
	v_add_u32_e32 v34, 0x18000, v220
	v_lshl_add_u64 v[32:33], s[4:5], 0, v[192:193]
	v_readfirstlane_b32 s8, v34
	v_lshlrev_b32_e32 v3, 7, v160
	v_lshl_add_u64 v[32:33], v[32:33], 0, s[0:1]
	s_mov_b32 m0, s8
	v_mov_b32_e32 v195, v193
	v_add_u32_e32 v34, 0x1a000, v220
	v_and_or_b32 v219, v3, s28, v0
	ds_read_b128 v[0:3], v218
	ds_read_b128 v[4:7], v218 offset:2048
	ds_read_b128 v[8:11], v218 offset:4096
	ds_read_b128 v[12:15], v218 offset:6144
	ds_read_b128 v[16:19], v219 offset:32768
	ds_read_b128 v[20:23], v219 offset:34816
	ds_read_b128 v[24:27], v219 offset:36864
	ds_read_b128 v[28:31], v219 offset:38912
	global_load_lds_dwordx4 v[32:33], off
	v_lshl_add_u64 v[32:33], s[4:5], 0, v[194:195]
	v_readfirstlane_b32 s8, v34
	v_lshl_add_u64 v[32:33], v[32:33], 0, s[0:1]
	s_mov_b32 m0, s8
	v_mov_b32_e32 v197, v193
	v_add_u32_e32 v34, 0x1c000, v220
	global_load_lds_dwordx4 v[32:33], off
	v_lshl_add_u64 v[32:33], s[4:5], 0, v[196:197]
	v_readfirstlane_b32 s8, v34
	v_lshl_add_u64 v[32:33], v[32:33], 0, s[0:1]
	s_mov_b32 m0, s8
	v_mov_b32_e32 v199, v193
	v_add_u32_e32 v34, 0x1e000, v220
	global_load_lds_dwordx4 v[32:33], off
	v_lshl_add_u64 v[32:33], s[4:5], 0, v[198:199]
	v_readfirstlane_b32 s4, v34
	v_lshl_add_u64 v[32:33], v[32:33], 0, s[0:1]
	s_mov_b32 m0, s4
	s_nop 0
	global_load_lds_dwordx4 v[32:33], off
	s_add_u32 s4, s82, s36
	s_addc_u32 s5, s83, s37
	v_add_u32_e32 v34, 0x10000, v220
	v_lshl_add_u64 v[32:33], s[4:5], 0, v[192:193]
	v_readfirstlane_b32 s8, v34
	v_lshl_add_u64 v[32:33], v[32:33], 0, s[0:1]
	s_mov_b32 m0, s8
	v_add_u32_e32 v34, 0x12000, v220
	global_load_lds_dwordx4 v[32:33], off
	v_lshl_add_u64 v[32:33], s[4:5], 0, v[194:195]
	v_readfirstlane_b32 s8, v34
	v_lshl_add_u64 v[32:33], v[32:33], 0, s[0:1]
	s_mov_b32 m0, s8
	v_add_u32_e32 v34, 0x14000, v220
	global_load_lds_dwordx4 v[32:33], off
	v_lshl_add_u64 v[32:33], s[4:5], 0, v[196:197]
	v_readfirstlane_b32 s8, v34
	v_lshl_add_u64 v[32:33], v[32:33], 0, s[0:1]
	s_mov_b32 m0, s8
	v_add_u32_e32 v34, 0x16000, v220
	global_load_lds_dwordx4 v[32:33], off
	v_lshl_add_u64 v[32:33], s[4:5], 0, v[198:199]
	v_readfirstlane_b32 s4, v34
	v_lshl_add_u64 v[32:33], v[32:33], 0, s[0:1]
	s_mov_b32 m0, s4
	s_mov_b32 s8, 0x10000
	global_load_lds_dwordx4 v[32:33], off
	ds_read_b128 v[32:35], v218 offset:8192
	ds_read_b128 v[36:39], v218 offset:10240
	ds_read_b128 v[40:43], v218 offset:12288
	ds_read_b128 v[44:47], v218 offset:14336
	s_setprio 1
	s_waitcnt lgkmcnt(0)
	v_mfma_f32_16x16x32_bf16 v[48:51], v[16:19], v[0:3], 0
	v_mfma_f32_16x16x32_bf16 v[52:55], v[20:23], v[0:3], 0
	v_mfma_f32_16x16x32_bf16 v[56:59], v[24:27], v[0:3], 0
	v_mfma_f32_16x16x32_bf16 v[60:63], v[28:31], v[0:3], 0
	v_mfma_f32_16x16x32_bf16 v[162:165], v[16:19], v[4:7], 0
	v_mfma_f32_16x16x32_bf16 v[166:169], v[20:23], v[4:7], 0
	v_mfma_f32_16x16x32_bf16 v[170:173], v[24:27], v[4:7], 0
	v_mfma_f32_16x16x32_bf16 v[174:177], v[28:31], v[4:7], 0
	v_mfma_f32_16x16x32_bf16 v[178:181], v[16:19], v[8:11], 0
	v_mfma_f32_16x16x32_bf16 v[182:185], v[20:23], v[8:11], 0
	v_mfma_f32_16x16x32_bf16 v[186:189], v[24:27], v[8:11], 0
	v_mfma_f32_16x16x32_bf16 v[222:225], v[28:31], v[8:11], 0
	v_mfma_f32_16x16x32_bf16 v[226:229], v[16:19], v[12:15], 0
	v_mfma_f32_16x16x32_bf16 v[230:233], v[20:23], v[12:15], 0
	v_mfma_f32_16x16x32_bf16 v[234:237], v[24:27], v[12:15], 0
	v_mfma_f32_16x16x32_bf16 v[238:241], v[28:31], v[12:15], 0
	s_setprio 0
	ds_read_b128 v[12:15], v218 offset:1024
	ds_read_b128 v[242:245], v218 offset:3072
	ds_read_b128 v[246:249], v218 offset:5120
	ds_read_b128 v[214:217], v218 offset:7168
	ds_read_b128 v[64:67], v219 offset:33792
	ds_read_b128 v[68:71], v219 offset:35840
	ds_read_b128 v[76:79], v219 offset:37888
	ds_read_b128 v[72:75], v219 offset:39936
	s_setprio 1
	v_mfma_f32_16x16x32_bf16 v[128:131], v[16:19], v[32:35], 0
	v_mfma_f32_16x16x32_bf16 v[124:127], v[20:23], v[32:35], 0
	v_mfma_f32_16x16x32_bf16 v[120:123], v[24:27], v[32:35], 0
	v_mfma_f32_16x16x32_bf16 v[116:119], v[28:31], v[32:35], 0
	v_mfma_f32_16x16x32_bf16 v[112:115], v[16:19], v[36:39], 0
	v_mfma_f32_16x16x32_bf16 v[108:111], v[20:23], v[36:39], 0
	v_mfma_f32_16x16x32_bf16 v[104:107], v[24:27], v[36:39], 0
	v_mfma_f32_16x16x32_bf16 v[100:103], v[28:31], v[36:39], 0
	v_mfma_f32_16x16x32_bf16 v[96:99], v[16:19], v[40:43], 0
	v_mfma_f32_16x16x32_bf16 v[92:95], v[20:23], v[40:43], 0
	v_mfma_f32_16x16x32_bf16 v[88:91], v[24:27], v[40:43], 0
	v_mfma_f32_16x16x32_bf16 v[84:87], v[28:31], v[40:43], 0
	v_mfma_f32_16x16x32_bf16 v[132:135], v[16:19], v[44:47], 0
	v_mfma_f32_16x16x32_bf16 v[136:139], v[20:23], v[44:47], 0
	v_mfma_f32_16x16x32_bf16 v[140:143], v[24:27], v[44:47], 0
	v_mfma_f32_16x16x32_bf16 v[80:83], v[28:31], v[44:47], 0
	s_setprio 0
	ds_read_b128 v[156:159], v218 offset:9216
	ds_read_b128 v[152:155], v218 offset:11264
	ds_read_b128 v[148:151], v218 offset:13312
	ds_read_b128 v[144:147], v218 offset:15360
	s_setprio 1
	s_waitcnt lgkmcnt(0)
; #define WAIT_V0() asm volatile("s_waitcnt vmcnt(0)" ::: "memory")
; #define G_STAGE_A(Ap, buf, kt) do { const char* ab_ = (const char*)(Ap) + (size_t)(kt) * 128; \
;       _Pragma("unroll") for (int i = 0; i < 4; ++i) \
;         __builtin_amdgcn_global_load_lds((const unsigned*)(ab_ + soff[i]), (LDSP unsigned*)(G_SA(buf) + wid * 1024 + i * 8192), 16, 0, 0); } while (0)
; #define G_STAGE_B(Bp, buf, kt) do { const char* bb_ = (const char*)(Bp) + (size_t)(kt) * 128; \
;       _Pragma("unroll") for (int i = 0; i < 4; ++i) \
;         __builtin_amdgcn_global_load_lds((const unsigned*)(bb_ + soff[i]), (LDSP unsigned*)(G_SB(buf) + wid * 1024 + i * 8192), 16, 0, 0); } while (0)
; #define G_RDA(AF, buf, ks, mh) do { _Pragma("unroll") for (int m = 0; m < 4; ++m) AF[m] = *(const LDSP bf16x8*)(G_SA(buf) + aoff + ((mh) * 4 + m) * 2048 + (ks) * 1024); } while (0)
; #define G_RDB(BF, buf, ks) do { _Pragma("unroll") for (int n = 0; n < 4; ++n) BF[n] = *(const LDSP bf16x8*)(G_SB(buf) + boff + n * 2048 + (ks) * 1024); } while (0)
; #define G_MMA(AF, BF, mh) do { __builtin_amdgcn_s_setprio(1); \
;             _Pragma("unroll") for (int m = 0; m < 4; ++m) _Pragma("unroll") for (int n = 0; n < 4; ++n) \
;                 acc[(mh) * 4 + m][n] = __builtin_amdgcn_mfma_f32_16x16x32_bf16(BF[n], AF[m], acc[(mh) * 4 + m][n], 0, 0, 0); \
;             __builtin_amdgcn_s_setprio(0); } while (0)
; template <int EK>
; DI void gemm_stream(const Params& p, int l, const bf16_t* __restrict__ A, const bf16_t* __restrict__ Bt, int M, int N, int K, ldsp_t shm) {
;     ...
;         for (int t = 0; t < nt; ++t) {
;             const int cur = t & 1;
;             G_RDA(Aa, cur, 0, 0); G_RDB(Bk0, cur, 0);
;             if (t + 1 < nt) G_STAGE_B(Bb, cur ^ 1, t + 1);
;             else if (has_next) G_STAGE_B(Bb2, cur ^ 1, 0);
;             G_SB0();
;             if (t > 0) G_MMA(Ab_, Bk1, 1);
;             G_SB0();
;             if (t + 1 < nt) G_STAGE_A(Ab, cur ^ 1, t + 1);
;             else if (has_next) G_STAGE_A(Ab2, cur ^ 1, 0);
;             G_RDA(Ab_, cur, 0, 1);
;             G_MMA(Aa, Bk0, 0); G_SB0();
;             G_RDA(Aa, cur, 1, 0); G_RDB(Bk1, cur, 1);
;             G_MMA(Ab_, Bk0, 1); G_SB0();
;             G_RDA(Ab_, cur, 1, 1);
;             G_MMA(Aa, Bk1, 0); G_SB0();
;             asm volatile("s_waitcnt lgkmcnt(0)" ::: "memory");
;             WAIT_V0(); __syncthreads();
	v_mfma_f32_16x16x32_bf16 v[0:3], v[64:67], v[12:15], v[48:51]
	v_mfma_f32_16x16x32_bf16 v[4:7], v[68:71], v[12:15], v[52:55]
	v_mfma_f32_16x16x32_bf16 v[8:11], v[76:79], v[12:15], v[56:59]
	v_mfma_f32_16x16x32_bf16 v[12:15], v[72:75], v[12:15], v[60:63]
	v_mfma_f32_16x16x32_bf16 v[16:19], v[64:67], v[242:245], v[162:165]
	v_mfma_f32_16x16x32_bf16 v[20:23], v[68:71], v[242:245], v[166:169]
	v_mfma_f32_16x16x32_bf16 v[24:27], v[76:79], v[242:245], v[170:173]
	v_mfma_f32_16x16x32_bf16 v[28:31], v[72:75], v[242:245], v[174:177]
	v_mfma_f32_16x16x32_bf16 v[32:35], v[64:67], v[246:249], v[178:181]
	v_mfma_f32_16x16x32_bf16 v[36:39], v[68:71], v[246:249], v[182:185]
	v_mfma_f32_16x16x32_bf16 v[40:43], v[76:79], v[246:249], v[186:189]
	v_mfma_f32_16x16x32_bf16 v[44:47], v[72:75], v[246:249], v[222:225]
	v_mfma_f32_16x16x32_bf16 v[48:51], v[64:67], v[214:217], v[226:229]
	v_mfma_f32_16x16x32_bf16 v[52:55], v[68:71], v[214:217], v[230:233]
	v_mfma_f32_16x16x32_bf16 v[56:59], v[76:79], v[214:217], v[234:237]
	v_mfma_f32_16x16x32_bf16 v[60:63], v[72:75], v[214:217], v[238:241]
	s_setprio 0
	v_lshlrev_b32_e32 v160, 8, v160
	s_movk_i32 s9, 0x8000
	v_readlane_b32 s4, v255, 10
	v_lshlrev_b32_e32 v162, 4, v200
	v_lshlrev_b32_e32 v164, 4, v201
	v_lshlrev_b32_e32 v167, 4, v204
	v_and_or_b32 v160, v160, s9, v191
	v_lshlrev_b32_e32 v166, 11, v161
	s_add_u32 s4, s4, s46
	v_readlane_b32 s5, v255, 7
	v_and_or_b32 v162, v162, s9, v191
	v_and_or_b32 v164, v164, s9, v191
	v_and_or_b32 v167, v167, s9, v191
	s_waitcnt lgkmcnt(0)
	v_or3_b32 v168, v160, v166, v190
	v_mov_b32_e32 v169, v193
	s_addc_u32 s5, s5, s47
	v_or3_b32 v170, v162, v166, v190
	v_mov_b32_e32 v171, v193
	v_or3_b32 v172, v164, v166, v190
	v_mov_b32_e32 v173, v193
	v_or3_b32 v174, v167, v166, v190
	v_mov_b32_e32 v175, v193
	s_waitcnt vmcnt(0)
	v_writelane_b32 v255, s52, 12
	v_writelane_b32 v255, s53, 13
	v_writelane_b32 v255, s64, 14
	v_writelane_b32 v255, s65, 15
	v_writelane_b32 v255, s30, 16
	s_mov_b64 s[64:65], s[4:5]
	s_add_u32 s4, s38, s36
	s_addc_u32 s5, s39, s37
	s_mov_b64 s[52:53], s[4:5]
	s_mov_b64 s[4:5], 0
	s_waitcnt vmcnt(0)
	v_lshrrev_b32_e32 v164, 6, v252
	v_lshlrev_b32_e32 v164, 10, v164
	s_nop 0
	v_readfirstlane_b32 s30, v164
	v_and_b32_e32 v165, 63, v252
	v_lshlrev_b32_e32 v165, 4, v165
	s_barrier
.LBB0_264:
	s_and_b32 s9, s8, 0x10000
	v_add_u32_e32 v221, s9, v218
	v_or_b32_e32 v226, s9, v219
	s_xor_b32 s9, s9, 0x10000
	s_add_u32 s9, s9, s30
	ds_read_b128 v[176:179], v221
	ds_read_b128 v[180:183], v221 offset:2048
	ds_read_b128 v[184:187], v221 offset:4096
	ds_read_b128 v[188:191], v221 offset:6144
	s_add_u32 m0, s9, 0x8000
	ds_read_b128 v[204:207], v226 offset:32768
	global_load_lds_dwordx4 v168, s[64:65]
	s_add_u32 m0, s9, 0xa000
	ds_read_b128 v[210:213], v226 offset:34816
	global_load_lds_dwordx4 v170, s[64:65]
	s_add_u32 m0, s9, 0xc000
	ds_read_b128 v[214:217], v226 offset:36864
	global_load_lds_dwordx4 v172, s[64:65]
	s_add_u32 m0, s9, 0xe000
	ds_read_b128 v[222:225], v226 offset:38912
	global_load_lds_dwordx4 v174, s[64:65]
	s_setprio 1
	v_mfma_f32_16x16x32_bf16 v[128:131], v[64:67], v[156:159], v[128:131]
	v_mfma_f32_16x16x32_bf16 v[124:127], v[68:71], v[156:159], v[124:127]
	v_mfma_f32_16x16x32_bf16 v[120:123], v[76:79], v[156:159], v[120:123]
	v_mfma_f32_16x16x32_bf16 v[116:119], v[72:75], v[156:159], v[116:119]
	v_mfma_f32_16x16x32_bf16 v[112:115], v[64:67], v[152:155], v[112:115]
	v_mfma_f32_16x16x32_bf16 v[108:111], v[68:71], v[152:155], v[108:111]
	v_mfma_f32_16x16x32_bf16 v[104:107], v[76:79], v[152:155], v[104:107]
	v_mfma_f32_16x16x32_bf16 v[100:103], v[72:75], v[152:155], v[100:103]
	v_mfma_f32_16x16x32_bf16 v[96:99], v[64:67], v[148:151], v[96:99]
	v_mfma_f32_16x16x32_bf16 v[92:95], v[68:71], v[148:151], v[92:95]
	v_mfma_f32_16x16x32_bf16 v[88:91], v[76:79], v[148:151], v[88:91]
	v_mfma_f32_16x16x32_bf16 v[84:87], v[72:75], v[148:151], v[84:87]
	v_mfma_f32_16x16x32_bf16 v[132:135], v[64:67], v[144:147], v[132:135]
	v_mfma_f32_16x16x32_bf16 v[136:139], v[68:71], v[144:147], v[136:139]
	v_mfma_f32_16x16x32_bf16 v[140:143], v[76:79], v[144:147], v[140:143]
	v_mfma_f32_16x16x32_bf16 v[80:83], v[72:75], v[144:147], v[80:83]
	s_setprio 0
	s_add_u32 m0, s9, 0x0
	s_nop 0
	global_load_lds_dwordx4 v168, s[52:53]
	s_add_u32 m0, s9, 0x2000
	s_nop 0
	global_load_lds_dwordx4 v170, s[52:53]
	s_add_u32 m0, s9, 0x4000
	s_nop 0
	global_load_lds_dwordx4 v172, s[52:53]
	s_add_u32 m0, s9, 0x6000
	s_nop 0
	global_load_lds_dwordx4 v174, s[52:53]
	ds_read_b128 v[144:147], v221 offset:8192
	ds_read_b128 v[148:151], v221 offset:10240
	ds_read_b128 v[152:155], v221 offset:12288
	ds_read_b128 v[156:159], v221 offset:14336
	s_setprio 1
	s_waitcnt lgkmcnt(4)
; #define WAIT_V0() asm volatile("s_waitcnt vmcnt(0)" ::: "memory")
; #define G_STAGE_B(Bp, buf, kt) do { const char* bb_ = (const char*)(Bp) + (size_t)(kt) * 128; \
;       _Pragma("unroll") for (int i = 0; i < 4; ++i) \
;         __builtin_amdgcn_global_load_lds((const unsigned*)(bb_ + soff[i]), (LDSP unsigned*)(G_SB(buf) + wid * 1024 + i * 8192), 16, 0, 0); } while (0)
; #define G_RDA(AF, buf, ks, mh) do { _Pragma("unroll") for (int m = 0; m < 4; ++m) AF[m] = *(const LDSP bf16x8*)(G_SA(buf) + aoff + ((mh) * 4 + m) * 2048 + (ks) * 1024); } while (0)
; #define G_RDB(BF, buf, ks) do { _Pragma("unroll") for (int n = 0; n < 4; ++n) BF[n] = *(const LDSP bf16x8*)(G_SB(buf) + boff + n * 2048 + (ks) * 1024); } while (0)
; #define G_MMA(AF, BF, mh) do { __builtin_amdgcn_s_setprio(1); \
;             _Pragma("unroll") for (int m = 0; m < 4; ++m) _Pragma("unroll") for (int n = 0; n < 4; ++n) \
;                 acc[(mh) * 4 + m][n] = __builtin_amdgcn_mfma_f32_16x16x32_bf16(BF[n], AF[m], acc[(mh) * 4 + m][n], 0, 0, 0); \
;             __builtin_amdgcn_s_setprio(0); } while (0)
; #define G_SB0() __builtin_amdgcn_sched_barrier(0)
; template <int EK>
; DI void gemm_stream(const Params& p, int l, const bf16_t* __restrict__ A, const bf16_t* __restrict__ Bt, int M, int N, int K, ldsp_t shm) {
;     ...
;             G_RDA(Aa, cur, 0, 0); G_RDB(Bk0, cur, 0);
;             if (t + 1 < nt) G_STAGE_B(Bb, cur ^ 1, t + 1);
;             else if (has_next) G_STAGE_B(Bb2, cur ^ 1, 0);
;     ...
;             G_MMA(Aa, Bk0, 0); G_SB0();
;             G_RDA(Aa, cur, 1, 0); G_RDB(Bk1, cur, 1);
;             G_MMA(Ab_, Bk0, 1); G_SB0();
;             G_RDA(Ab_, cur, 1, 1);
;             G_MMA(Aa, Bk1, 0); G_SB0();
;             asm volatile("s_waitcnt lgkmcnt(0)" ::: "memory");
;             WAIT_V0(); __syncthreads();
	v_mfma_f32_16x16x32_bf16 v[0:3], v[204:207], v[176:179], v[0:3]
	v_mfma_f32_16x16x32_bf16 v[4:7], v[210:213], v[176:179], v[4:7]
	v_mfma_f32_16x16x32_bf16 v[8:11], v[214:217], v[176:179], v[8:11]
	v_mfma_f32_16x16x32_bf16 v[12:15], v[222:225], v[176:179], v[12:15]
	v_mfma_f32_16x16x32_bf16 v[16:19], v[204:207], v[180:183], v[16:19]
	v_mfma_f32_16x16x32_bf16 v[20:23], v[210:213], v[180:183], v[20:23]
	v_mfma_f32_16x16x32_bf16 v[24:27], v[214:217], v[180:183], v[24:27]
	v_mfma_f32_16x16x32_bf16 v[28:31], v[222:225], v[180:183], v[28:31]
	v_mfma_f32_16x16x32_bf16 v[32:35], v[204:207], v[184:187], v[32:35]
	v_mfma_f32_16x16x32_bf16 v[36:39], v[210:213], v[184:187], v[36:39]
	v_mfma_f32_16x16x32_bf16 v[40:43], v[214:217], v[184:187], v[40:43]
	v_mfma_f32_16x16x32_bf16 v[44:47], v[222:225], v[184:187], v[44:47]
	v_mfma_f32_16x16x32_bf16 v[48:51], v[204:207], v[188:191], v[48:51]
	v_mfma_f32_16x16x32_bf16 v[52:55], v[210:213], v[188:191], v[52:55]
	v_mfma_f32_16x16x32_bf16 v[56:59], v[214:217], v[188:191], v[56:59]
	v_mfma_f32_16x16x32_bf16 v[60:63], v[222:225], v[188:191], v[60:63]
	s_setprio 0
	ds_read_b128 v[176:179], v221 offset:1024
	ds_read_b128 v[180:183], v221 offset:3072
	ds_read_b128 v[184:187], v221 offset:5120
	ds_read_b128 v[188:191], v221 offset:7168
	ds_read_b128 v[64:67], v226 offset:33792
	ds_read_b128 v[68:71], v226 offset:35840
	ds_read_b128 v[76:79], v226 offset:37888
	ds_read_b128 v[72:75], v226 offset:39936
	s_setprio 1
	s_waitcnt lgkmcnt(8)
	v_mfma_f32_16x16x32_bf16 v[128:131], v[204:207], v[144:147], v[128:131]
	v_mfma_f32_16x16x32_bf16 v[124:127], v[210:213], v[144:147], v[124:127]
	v_mfma_f32_16x16x32_bf16 v[120:123], v[214:217], v[144:147], v[120:123]
	v_mfma_f32_16x16x32_bf16 v[116:119], v[222:225], v[144:147], v[116:119]
	v_mfma_f32_16x16x32_bf16 v[112:115], v[204:207], v[148:151], v[112:115]
	v_mfma_f32_16x16x32_bf16 v[108:111], v[210:213], v[148:151], v[108:111]
	v_mfma_f32_16x16x32_bf16 v[104:107], v[214:217], v[148:151], v[104:107]
	v_mfma_f32_16x16x32_bf16 v[100:103], v[222:225], v[148:151], v[100:103]
	v_mfma_f32_16x16x32_bf16 v[96:99], v[204:207], v[152:155], v[96:99]
	v_mfma_f32_16x16x32_bf16 v[92:95], v[210:213], v[152:155], v[92:95]
	v_mfma_f32_16x16x32_bf16 v[88:91], v[214:217], v[152:155], v[88:91]
	v_mfma_f32_16x16x32_bf16 v[84:87], v[222:225], v[152:155], v[84:87]
	v_mfma_f32_16x16x32_bf16 v[132:135], v[204:207], v[156:159], v[132:135]
	v_mfma_f32_16x16x32_bf16 v[136:139], v[210:213], v[156:159], v[136:139]
	v_mfma_f32_16x16x32_bf16 v[140:143], v[214:217], v[156:159], v[140:143]
	v_mfma_f32_16x16x32_bf16 v[80:83], v[222:225], v[156:159], v[80:83]
	s_setprio 0
	ds_read_b128 v[156:159], v221 offset:9216
	ds_read_b128 v[152:155], v221 offset:11264
	ds_read_b128 v[148:151], v221 offset:13312
	ds_read_b128 v[144:147], v221 offset:15360
	s_setprio 1
	s_waitcnt lgkmcnt(4)
	v_mfma_f32_16x16x32_bf16 v[0:3], v[64:67], v[176:179], v[0:3]
	v_mfma_f32_16x16x32_bf16 v[4:7], v[68:71], v[176:179], v[4:7]
	v_mfma_f32_16x16x32_bf16 v[8:11], v[76:79], v[176:179], v[8:11]
	v_mfma_f32_16x16x32_bf16 v[12:15], v[72:75], v[176:179], v[12:15]
	v_mfma_f32_16x16x32_bf16 v[16:19], v[64:67], v[180:183], v[16:19]
	v_mfma_f32_16x16x32_bf16 v[20:23], v[68:71], v[180:183], v[20:23]
	v_mfma_f32_16x16x32_bf16 v[24:27], v[76:79], v[180:183], v[24:27]
	v_mfma_f32_16x16x32_bf16 v[28:31], v[72:75], v[180:183], v[28:31]
	v_mfma_f32_16x16x32_bf16 v[32:35], v[64:67], v[184:187], v[32:35]
	v_mfma_f32_16x16x32_bf16 v[36:39], v[68:71], v[184:187], v[36:39]
	v_mfma_f32_16x16x32_bf16 v[40:43], v[76:79], v[184:187], v[40:43]
	v_mfma_f32_16x16x32_bf16 v[44:47], v[72:75], v[184:187], v[44:47]
	v_mfma_f32_16x16x32_bf16 v[48:51], v[64:67], v[188:191], v[48:51]
	v_mfma_f32_16x16x32_bf16 v[52:55], v[68:71], v[188:191], v[52:55]
	v_mfma_f32_16x16x32_bf16 v[56:59], v[76:79], v[188:191], v[56:59]
	v_mfma_f32_16x16x32_bf16 v[60:63], v[72:75], v[188:191], v[60:63]
	s_setprio 0
	s_waitcnt lgkmcnt(0)
	s_add_u32 s52, s52, 0x80
	s_addc_u32 s53, s53, 0
	s_add_u32 s64, s64, 0x80
	s_addc_u32 s65, s65, 0
	s_add_u32 s4, s4, 0x80
	s_addc_u32 s5, s5, 0
	s_add_i32 s8, s8, 0x10000
	s_cmpk_eq_i32 s4, 0x700
	s_waitcnt vmcnt(0)
	s_barrier
	s_cbranch_scc0 .LBB0_264
	v_readlane_b32 s52, v255, 12
	v_readlane_b32 s53, v255, 13
	v_readlane_b32 s64, v255, 14
	v_readlane_b32 s65, v255, 15
	v_readlane_b32 s30, v255, 16
	v_add_u32_e32 v160, 0x10000, v218
	v_add_u32_e32 v161, 0x10800, v218
	ds_read_b128 v[188:191], v160
	ds_read_b128 v[180:183], v161
	v_add_u32_e32 v160, 0x11000, v218
	v_add_u32_e32 v161, 0x11800, v218
	ds_read_b128 v[184:187], v160
	ds_read_b128 v[176:179], v161
	v_or_b32_e32 v160, 0x18000, v219
	v_add_u32_e32 v164, 0x18800, v219
	v_add_u32_e32 v168, 0x19000, v219
	v_add_u32_e32 v172, 0x19800, v219
	ds_read_b128 v[160:163], v160
	ds_read_b128 v[164:167], v164
	ds_read_b128 v[168:171], v168
	ds_read_b128 v[172:175], v172
	s_ashr_i32 s43, s42, 31
	v_cndmask_b32_e64 v200, 0, 1, s[6:7]
	v_cmp_ne_u32_e64 s[4:5], 1, v200
	s_andn2_b64 vcc, exec, s[6:7]
	s_lshl_b64 s[46:47], s[42:43], 19
	s_cbranch_vccnz .LBB0_267
	s_add_u32 s6, s14, s46
	s_addc_u32 s7, s15, s47
	v_add_u32_e32 v212, 0x8000, v220
	v_lshl_add_u64 v[200:201], s[6:7], 0, v[192:193]
	v_lshl_add_u64 v[204:205], s[6:7], 0, v[194:195]
	v_lshl_add_u64 v[206:207], s[6:7], 0, v[196:197]
	v_lshl_add_u64 v[210:211], s[6:7], 0, v[198:199]
	v_add_u32_e32 v215, 0xa000, v220
	v_readfirstlane_b32 s6, v212
	v_add_u32_e32 v214, 0xc000, v220
	s_mov_b32 m0, s6
	v_readfirstlane_b32 s6, v215
	v_add_u32_e32 v213, 0xe000, v220
	global_load_lds_dwordx4 v[200:201], off
	s_mov_b32 m0, s6
	v_readfirstlane_b32 s6, v214
	global_load_lds_dwordx4 v[204:205], off
	s_mov_b32 m0, s6
	v_readfirstlane_b32 s6, v213
	global_load_lds_dwordx4 v[206:207], off
	s_mov_b32 m0, s6
	s_nop 0
	global_load_lds_dwordx4 v[210:211], off
